# isel scores: de-serialised prologue loads + scalar relu-fma instead of packed; attention: epilogue z-load hoist, multi-buffered LDS fragment reads
# speedup vs baseline: 1.0256x; 1.0256x over previous
.LBB0_330:
	s_and_b32 s2, s45, 0xff
	s_ashr_i32 s1, s45, 9
	s_and_b32 s0, s45, 0x100
	s_xor_b32 s3, s2, 0x1ff
	s_cmp_eq_u32 s0, 0
	v_mov_b32_e32 v13, v212
	s_cselect_b32 s2, s2, s3
	s_lshl_b32 s29, s2, 3
	v_readfirstlane_b32 s0, v13
	s_lshl_b32 s49, s1, 12
	s_lshr_b32 s34, s2, 2
	s_ashr_i32 s0, s0, 6
	s_cmp_gt_i32 s0, s34
	v_and_b32_e32 v221, 63, v13
	s_cbranch_scc1 .LBB0_335
	s_or_b32 s6, s29, s49
	s_lshl_b32 s2, s2, 11
	s_lshl_b32 s4, s6, 1
	s_and_b32 s35, s2, 0xf000
	s_or_b32 s2, s4, 1
	s_ashr_i32 s3, s2, 31
	s_lshl_b64 s[38:39], s[2:3], 10
	s_or_b32 s2, s4, 2
	s_ashr_i32 s3, s2, 31
	s_lshl_b64 s[40:41], s[2:3], 10
	s_or_b32 s2, s4, 3
	s_ashr_i32 s3, s2, 31
	s_lshl_b64 s[42:43], s[2:3], 10
	s_ashr_i32 s2, s6, 8
	s_mulk_i32 s2, 0x49
	s_ashr_i32 s3, s2, 31
	s_lshl_b64 s[30:31], s[2:3], 17
	s_or_b32 s2, s4, 4
	s_ashr_i32 s3, s2, 31
	s_lshl_b64 s[20:21], s[2:3], 10
	s_or_b32 s2, s4, 5
	s_ashr_i32 s3, s2, 31
	s_lshl_b64 s[22:23], s[2:3], 10
	s_or_b32 s2, s4, 6
	s_ashr_i32 s3, s2, 31
	s_lshl_b64 s[24:25], s[2:3], 10
	s_or_b32 s2, s4, 7
	s_ashr_i32 s3, s2, 31
	s_lshl_b64 s[26:27], s[2:3], 10
	s_or_b32 s2, s4, 8
	s_ashr_i32 s3, s2, 31
	s_lshl_b64 s[12:13], s[2:3], 10
	s_or_b32 s2, s4, 9
	s_ashr_i32 s3, s2, 31
	s_lshl_b64 s[14:15], s[2:3], 10
	s_or_b32 s2, s4, 10
	s_ashr_i32 s5, s4, 31
	s_ashr_i32 s3, s2, 31
	s_lshl_b64 s[36:37], s[4:5], 10
	s_lshl_b64 s[16:17], s[2:3], 10
	s_or_b32 s2, s4, 11
	s_waitcnt vmcnt(0)
	s_ashr_i32 s3, s2, 31
	s_lshl_b64 s[18:19], s[2:3], 10
	s_or_b32 s2, s4, 12
	s_or_b32 s6, s4, 13
	s_or_b32 s8, s4, 14
	s_or_b32 s4, s4, 15
	s_ashr_i32 s5, s4, 31
	s_lshl_b64 s[10:11], s[4:5], 10
	s_lshl_b32 s4, s1, 7
	s_ashr_i32 s3, s2, 31
	s_ashr_i32 s7, s6, 31
	s_ashr_i32 s9, s8, 31
	s_ashr_i32 s5, s4, 31
	s_lshl_b64 s[2:3], s[2:3], 10
	s_lshl_b64 s[6:7], s[6:7], 10
	s_lshl_b64 s[8:9], s[8:9], 10
	s_lshl_b64 s[4:5], s[4:5], 12
	v_readlane_b32 s36, v237, 5
	v_readlane_b32 s37, v237, 6
	s_add_u32 s30, s36, s30
	s_addc_u32 s31, s37, s31
	s_mov_b32 s1, 0x1bb00000
	s_mov_b64 s[30:31], 0x1bb00800
	s_mov_b32 s30, 0x3d000000
	v_readlane_b32 s36, v237, 46
	s_movk_i32 s41, 0x3fff
	s_mov_b32 s40, 0x800000
	s_movk_i32 s39, 0x1e0
	v_readlane_b32 s38, v237, 45
	v_readlane_b32 s37, v237, 47
	s_mov_b64 s[20:21], 0x1bb00880
	s_mov_b64 s[12:13], 0x1bb00900
	s_mov_b64 s[2:3], 0x1bb00980
	v_readlane_b32 s2, v239, 12
	v_readlane_b32 s3, v239, 13
	s_add_u32 s2, s2, s4
	s_addc_u32 s3, s3, s5
	s_ashr_i32 s1, s0, 31
	s_lshl_b64 s[2:3], s[0:1], 12
	s_lshl_b32 s1, s0, 7
	s_add_i32 s1, 0, 0x10000
	s_add_u32 s1, s2, s4
	s_addc_u32 s3, s3, s5
	v_readlane_b32 s2, v237, 3
	s_add_u32 s2, s2, s1
	v_readlane_b32 s1, v237, 4
	s_addc_u32 s3, s1, s3
	s_mov_b32 s1, s0
	v_lshlrev_b32_e32 v0, 4, v221
	v_lshrrev_b32_e32 v12, 5, v221
	v_and_b32_e32 v4, 31, v13
	s_or_b32 s2, s29, s49
	v_readlane_b32 s4, v237, 5
	v_readlane_b32 s5, v237, 6
	s_lshr_b32 s3, s2, 8
	s_mulk_i32 s3, 0x49
	s_lshl_b32 s3, s3, 17
	s_add_u32 s3, s3, 0x1bb00000
	s_add_u32 s4, s4, s3
	s_addc_u32 s5, s5, 0
	s_lshl_b32 s3, s29, 8
	s_and_b32 s3, s3, 0xf000
	v_or_b32_e32 v222, s29, v12
	v_lshlrev_b32_e32 v2, 5, v222
	v_and_b32_e32 v2, 0x120, v2
	v_or_b32_e32 v2, s3, v2
	v_lshlrev_b32_e32 v2, 1, v2
	v_mov_b32_e32 v3, v1
	v_lshl_add_u64 v[6:7], s[4:5], 0, v[2:3]
	global_load_dwordx4 v[18:21], v[6:7], off offset:2048
	global_load_dwordx4 v[22:25], v[6:7], off offset:2064
	global_load_dwordx4 v[26:29], v[6:7], off offset:2176
	global_load_dwordx4 v[30:33], v[6:7], off offset:2192
	global_load_dwordx4 v[34:37], v[6:7], off offset:2304
	global_load_dwordx4 v[38:41], v[6:7], off offset:2320
	global_load_dwordx4 v[42:45], v[6:7], off offset:2432
	global_load_dwordx4 v[46:49], v[6:7], off offset:2448
	s_lshl_b32 s3, s2, 11
	s_add_u32 s4, s82, s3
	s_addc_u32 s5, s83, 0
	s_add_u32 s4, s4, 0x1000
	s_addc_u32 s5, s5, 0
	v_lshl_add_u64 v[8:9], s[4:5], 0, v[0:1]
	s_add_u32 s4, s4, 0x2000
	s_addc_u32 s5, s5, 0
	v_lshl_add_u64 v[10:11], s[4:5], 0, v[0:1]
	global_load_dwordx4 v[66:69], v[8:9], off offset:-4096
	global_load_dwordx4 v[70:73], v[8:9], off offset:-3072
	global_load_dwordx4 v[74:77], v[8:9], off offset:-2048
	global_load_dwordx4 v[78:81], v[8:9], off offset:-1024
	global_load_dwordx4 v[82:85], v[8:9], off
	global_load_dwordx4 v[86:89], v[8:9], off offset:1024
	global_load_dwordx4 v[90:93], v[8:9], off offset:2048
	global_load_dwordx4 v[94:97], v[8:9], off offset:3072
	global_load_dwordx4 v[98:101], v[10:11], off offset:-4096
	global_load_dwordx4 v[102:105], v[10:11], off offset:-3072
	global_load_dwordx4 v[106:109], v[10:11], off offset:-2048
	global_load_dwordx4 v[110:113], v[10:11], off offset:-1024
	global_load_dwordx4 v[114:117], v[10:11], off
	global_load_dwordx4 v[118:121], v[10:11], off offset:1024
	global_load_dwordx4 v[122:125], v[10:11], off offset:2048
	global_load_dwordx4 v[126:129], v[10:11], off offset:3072
	v_readlane_b32 s4, v239, 12
	v_readlane_b32 s5, v239, 13
	s_lshl_b32 s3, s49, 7
	s_lshl_b32 s2, s0, 12
	s_add_u32 s3, s3, s2
	s_add_u32 s4, s4, s3
	s_addc_u32 s5, s5, 0
	v_lshl_add_u64 v[2:3], s[4:5], 0, v[0:1]
	global_load_dwordx4 v[130:133], v[2:3], off
	global_load_dwordx4 v[134:137], v[2:3], off offset:1024
	global_load_dwordx4 v[138:141], v[2:3], off offset:2048
	global_load_dwordx4 v[142:145], v[2:3], off offset:3072
	s_add_u32 s4, s4, 0x8800
	s_addc_u32 s5, s5, 0
	v_lshl_add_u64 v[210:211], s[4:5], 0, v[0:1]
	v_or_b32_e32 v223, 2, v222
	v_or_b32_e32 v224, 4, v222
	v_or_b32_e32 v225, 6, v222
	s_lshl_b32 s2, s0, 7
	v_lshlrev_b32_e32 v2, 14, v12
	v_lshl_or_b32 v2, v4, 2, v2
	v_add_u32_e32 v2, s2, v2
	v_add_u32_e32 v227, 0x10000, v2
	v_lshl_or_b32 v226, s0, 5, v4
	s_waitcnt vmcnt(20)
	v_and_b32_e32 v3, 0xffff0000, v18
	v_lshlrev_b32_e32 v2, 16, v18
	v_mul_f32_e32 v147, s30, v3
	v_mul_f32_e32 v146, s30, v2
	v_and_b32_e32 v3, 0xffff0000, v19
	v_lshlrev_b32_e32 v2, 16, v19
	v_mul_f32_e32 v149, s30, v3
	v_mul_f32_e32 v148, s30, v2
	v_and_b32_e32 v3, 0xffff0000, v20
	v_lshlrev_b32_e32 v2, 16, v20
	v_mul_f32_e32 v151, s30, v3
	v_mul_f32_e32 v150, s30, v2
	v_and_b32_e32 v3, 0xffff0000, v21
	v_lshlrev_b32_e32 v2, 16, v21
	v_mul_f32_e32 v153, s30, v3
	v_mul_f32_e32 v152, s30, v2
	v_and_b32_e32 v3, 0xffff0000, v22
	v_lshlrev_b32_e32 v2, 16, v22
	v_mul_f32_e32 v155, s30, v3
	v_mul_f32_e32 v154, s30, v2
	v_and_b32_e32 v3, 0xffff0000, v23
	v_lshlrev_b32_e32 v2, 16, v23
	v_mul_f32_e32 v157, s30, v3
	v_mul_f32_e32 v156, s30, v2
	v_and_b32_e32 v3, 0xffff0000, v24
	v_lshlrev_b32_e32 v2, 16, v24
	v_mul_f32_e32 v159, s30, v3
	v_mul_f32_e32 v158, s30, v2
	v_and_b32_e32 v3, 0xffff0000, v25
	v_lshlrev_b32_e32 v2, 16, v25
	v_mul_f32_e32 v161, s30, v3
	v_mul_f32_e32 v160, s30, v2
	v_and_b32_e32 v3, 0xffff0000, v26
	v_lshlrev_b32_e32 v2, 16, v26
	v_mul_f32_e32 v163, s30, v3
	v_mul_f32_e32 v162, s30, v2
	v_and_b32_e32 v3, 0xffff0000, v27
	v_lshlrev_b32_e32 v2, 16, v27
	v_mul_f32_e32 v165, s30, v3
	v_mul_f32_e32 v164, s30, v2
	v_and_b32_e32 v3, 0xffff0000, v28
	v_lshlrev_b32_e32 v2, 16, v28
	v_mul_f32_e32 v167, s30, v3
	v_mul_f32_e32 v166, s30, v2
	v_and_b32_e32 v3, 0xffff0000, v29
	v_lshlrev_b32_e32 v2, 16, v29
	v_mul_f32_e32 v169, s30, v3
	v_mul_f32_e32 v168, s30, v2
	v_and_b32_e32 v3, 0xffff0000, v30
	v_lshlrev_b32_e32 v2, 16, v30
	v_mul_f32_e32 v171, s30, v3
	v_mul_f32_e32 v170, s30, v2
	v_and_b32_e32 v3, 0xffff0000, v31
	v_lshlrev_b32_e32 v2, 16, v31
	v_mul_f32_e32 v173, s30, v3
	v_mul_f32_e32 v172, s30, v2
	v_and_b32_e32 v3, 0xffff0000, v32
	v_lshlrev_b32_e32 v2, 16, v32
	v_mul_f32_e32 v175, s30, v3
	v_mul_f32_e32 v174, s30, v2
	v_and_b32_e32 v3, 0xffff0000, v33
	v_lshlrev_b32_e32 v2, 16, v33
	v_mul_f32_e32 v177, s30, v3
	v_mul_f32_e32 v176, s30, v2
	v_and_b32_e32 v3, 0xffff0000, v34
	v_lshlrev_b32_e32 v2, 16, v34
	v_mul_f32_e32 v179, s30, v3
	v_mul_f32_e32 v178, s30, v2
	v_and_b32_e32 v3, 0xffff0000, v35
	v_lshlrev_b32_e32 v2, 16, v35
	v_mul_f32_e32 v181, s30, v3
	v_mul_f32_e32 v180, s30, v2
	v_and_b32_e32 v3, 0xffff0000, v36
	v_lshlrev_b32_e32 v2, 16, v36
	v_mul_f32_e32 v183, s30, v3
	v_mul_f32_e32 v182, s30, v2
	v_and_b32_e32 v3, 0xffff0000, v37
	v_lshlrev_b32_e32 v2, 16, v37
	v_mul_f32_e32 v185, s30, v3
	v_mul_f32_e32 v184, s30, v2
	v_and_b32_e32 v3, 0xffff0000, v38
	v_lshlrev_b32_e32 v2, 16, v38
	v_mul_f32_e32 v187, s30, v3
	v_mul_f32_e32 v186, s30, v2
	v_and_b32_e32 v3, 0xffff0000, v39
	v_lshlrev_b32_e32 v2, 16, v39
	v_mul_f32_e32 v189, s30, v3
	v_mul_f32_e32 v188, s30, v2
	v_and_b32_e32 v3, 0xffff0000, v40
	v_lshlrev_b32_e32 v2, 16, v40
	v_mul_f32_e32 v191, s30, v3
	v_mul_f32_e32 v190, s30, v2
	v_and_b32_e32 v3, 0xffff0000, v41
	v_lshlrev_b32_e32 v2, 16, v41
	v_mul_f32_e32 v193, s30, v3
	v_mul_f32_e32 v192, s30, v2
	v_and_b32_e32 v3, 0xffff0000, v42
	v_lshlrev_b32_e32 v2, 16, v42
	v_mul_f32_e32 v195, s30, v3
	v_mul_f32_e32 v194, s30, v2
	v_and_b32_e32 v3, 0xffff0000, v43
	v_lshlrev_b32_e32 v2, 16, v43
	v_mul_f32_e32 v197, s30, v3
	v_mul_f32_e32 v196, s30, v2
	v_and_b32_e32 v3, 0xffff0000, v44
	v_lshlrev_b32_e32 v2, 16, v44
	v_mul_f32_e32 v199, s30, v3
	v_mul_f32_e32 v198, s30, v2
	v_and_b32_e32 v3, 0xffff0000, v45
	v_lshlrev_b32_e32 v2, 16, v45
	v_mul_f32_e32 v201, s30, v3
	v_mul_f32_e32 v200, s30, v2
	v_and_b32_e32 v3, 0xffff0000, v46
	v_lshlrev_b32_e32 v2, 16, v46
	v_mul_f32_e32 v203, s30, v3
	v_mul_f32_e32 v202, s30, v2
	v_and_b32_e32 v3, 0xffff0000, v47
	v_lshlrev_b32_e32 v2, 16, v47
	v_mul_f32_e32 v205, s30, v3
	v_mul_f32_e32 v204, s30, v2
	v_and_b32_e32 v3, 0xffff0000, v48
	v_lshlrev_b32_e32 v2, 16, v48
	v_mul_f32_e32 v207, s30, v3
	v_mul_f32_e32 v206, s30, v2
	v_and_b32_e32 v3, 0xffff0000, v49
	v_lshlrev_b32_e32 v2, 16, v49
	v_mul_f32_e32 v209, s30, v3
	v_mul_f32_e32 v208, s30, v2
	s_branch .LBB0_333
.LBB0_332:
	s_nop 7
	v_max_f32_e32 v50, 0, v50
	v_max_f32_e32 v34, 0, v34
	v_max_f32_e32 v18, 0, v18
	v_max_f32_e32 v2, 0, v2
	v_mul_f32_e32 v228, v146, v50
	v_mul_f32_e32 v229, v162, v34
	v_mul_f32_e32 v230, v178, v18
	v_mul_f32_e32 v231, v194, v2
	v_max_f32_e32 v51, 0, v51
	v_max_f32_e32 v35, 0, v35
	v_max_f32_e32 v19, 0, v19
	v_max_f32_e32 v3, 0, v3
	v_fmac_f32_e32 v228, v147, v51
	v_fmac_f32_e32 v229, v163, v35
	v_fmac_f32_e32 v230, v179, v19
	v_fmac_f32_e32 v231, v195, v3
	v_max_f32_e32 v52, 0, v52
	v_max_f32_e32 v36, 0, v36
	v_max_f32_e32 v20, 0, v20
	v_max_f32_e32 v4, 0, v4
	v_fmac_f32_e32 v228, v148, v52
	v_fmac_f32_e32 v229, v164, v36
	v_fmac_f32_e32 v230, v180, v20
	v_fmac_f32_e32 v231, v196, v4
	v_max_f32_e32 v53, 0, v53
	v_max_f32_e32 v37, 0, v37
	v_max_f32_e32 v21, 0, v21
	v_max_f32_e32 v5, 0, v5
	v_fmac_f32_e32 v228, v149, v53
	v_fmac_f32_e32 v229, v165, v37
	v_fmac_f32_e32 v230, v181, v21
	v_fmac_f32_e32 v231, v197, v5
	v_max_f32_e32 v54, 0, v54
	v_max_f32_e32 v38, 0, v38
	v_max_f32_e32 v22, 0, v22
	v_max_f32_e32 v6, 0, v6
	v_fmac_f32_e32 v228, v150, v54
	v_fmac_f32_e32 v229, v166, v38
	v_fmac_f32_e32 v230, v182, v22
	v_fmac_f32_e32 v231, v198, v6
	v_max_f32_e32 v55, 0, v55
	v_max_f32_e32 v39, 0, v39
	v_max_f32_e32 v23, 0, v23
	v_max_f32_e32 v7, 0, v7
	v_fmac_f32_e32 v228, v151, v55
	v_fmac_f32_e32 v229, v167, v39
	v_fmac_f32_e32 v230, v183, v23
	v_fmac_f32_e32 v231, v199, v7
	v_max_f32_e32 v56, 0, v56
	v_max_f32_e32 v40, 0, v40
	v_max_f32_e32 v24, 0, v24
	v_max_f32_e32 v8, 0, v8
	v_fmac_f32_e32 v228, v152, v56
	v_fmac_f32_e32 v229, v168, v40
	v_fmac_f32_e32 v230, v184, v24
	v_fmac_f32_e32 v231, v200, v8
	v_max_f32_e32 v57, 0, v57
	v_max_f32_e32 v41, 0, v41
	v_max_f32_e32 v25, 0, v25
	v_max_f32_e32 v9, 0, v9
	v_fmac_f32_e32 v228, v153, v57
	v_fmac_f32_e32 v229, v169, v41
	v_fmac_f32_e32 v230, v185, v25
	v_fmac_f32_e32 v231, v201, v9
	v_max_f32_e32 v58, 0, v58
	v_max_f32_e32 v42, 0, v42
	v_max_f32_e32 v26, 0, v26
	v_max_f32_e32 v10, 0, v10
	v_fmac_f32_e32 v228, v154, v58
	v_fmac_f32_e32 v229, v170, v42
	v_fmac_f32_e32 v230, v186, v26
	v_fmac_f32_e32 v231, v202, v10
	v_max_f32_e32 v59, 0, v59
	v_max_f32_e32 v43, 0, v43
	v_max_f32_e32 v27, 0, v27
	v_max_f32_e32 v11, 0, v11
	v_fmac_f32_e32 v228, v155, v59
	v_fmac_f32_e32 v229, v171, v43
	v_fmac_f32_e32 v230, v187, v27
	v_fmac_f32_e32 v231, v203, v11
	v_max_f32_e32 v60, 0, v60
	v_max_f32_e32 v44, 0, v44
	v_max_f32_e32 v28, 0, v28
	v_max_f32_e32 v12, 0, v12
	v_fmac_f32_e32 v228, v156, v60
	v_fmac_f32_e32 v229, v172, v44
	v_fmac_f32_e32 v230, v188, v28
	v_fmac_f32_e32 v231, v204, v12
	v_max_f32_e32 v61, 0, v61
	v_max_f32_e32 v45, 0, v45
	v_max_f32_e32 v29, 0, v29
	v_max_f32_e32 v13, 0, v13
	v_fmac_f32_e32 v228, v157, v61
	v_fmac_f32_e32 v229, v173, v45
	v_fmac_f32_e32 v230, v189, v29
	v_fmac_f32_e32 v231, v205, v13
	v_max_f32_e32 v62, 0, v62
	v_max_f32_e32 v46, 0, v46
	v_max_f32_e32 v30, 0, v30
	v_max_f32_e32 v14, 0, v14
	v_fmac_f32_e32 v228, v158, v62
	v_fmac_f32_e32 v229, v174, v46
	v_fmac_f32_e32 v230, v190, v30
	v_fmac_f32_e32 v231, v206, v14
	v_max_f32_e32 v63, 0, v63
	v_max_f32_e32 v47, 0, v47
	v_max_f32_e32 v31, 0, v31
	v_max_f32_e32 v15, 0, v15
	v_fmac_f32_e32 v228, v159, v63
	v_fmac_f32_e32 v229, v175, v47
	v_fmac_f32_e32 v230, v191, v31
	v_fmac_f32_e32 v231, v207, v15
	v_max_f32_e32 v64, 0, v64
	v_max_f32_e32 v48, 0, v48
	v_max_f32_e32 v32, 0, v32
	v_max_f32_e32 v16, 0, v16
	v_fmac_f32_e32 v228, v160, v64
	v_fmac_f32_e32 v229, v176, v48
	v_fmac_f32_e32 v230, v192, v32
	v_fmac_f32_e32 v231, v208, v16
	v_max_f32_e32 v65, 0, v65
	v_max_f32_e32 v49, 0, v49
	v_max_f32_e32 v33, 0, v33
	v_max_f32_e32 v17, 0, v17
	v_fmac_f32_e32 v228, v161, v65
	v_fmac_f32_e32 v229, v177, v49
	v_fmac_f32_e32 v230, v193, v33
	v_fmac_f32_e32 v231, v209, v17
	v_ashrrev_i32_e32 v50, 31, v228
	v_ashrrev_i32_e32 v51, 31, v229
	v_ashrrev_i32_e32 v52, 31, v230
	v_ashrrev_i32_e32 v53, 31, v231
	v_cmp_le_i32_e32 vcc, v226, v222
	v_or_b32_e32 v50, v217, v50
	v_or_b32_e32 v51, v217, v51
	v_xor_b32_e32 v228, v50, v228
	v_cndmask_b32_e32 v228, 0, v228, vcc
	v_cmp_le_i32_e32 vcc, v226, v223
	v_or_b32_e32 v52, v217, v52
	v_xor_b32_e32 v229, v51, v229
	v_cndmask_b32_e32 v229, 0, v229, vcc
	v_cmp_le_i32_e32 vcc, v226, v224
	v_or_b32_e32 v53, v217, v53
	v_xor_b32_e32 v230, v52, v230
	v_cndmask_b32_e32 v230, 0, v230, vcc
	v_cmp_le_i32_e32 vcc, v226, v225
	v_xor_b32_e32 v231, v53, v231
	v_add_u32_e32 v0, 0xffff0000, v227
	v_cndmask_b32_e32 v231, 0, v231, vcc
	ds_write2st64_b32 v0, v228, v229 offset1:128
	ds_write2st64_b32 v227, v230, v231 offset1:128
	s_mov_b64 s[4:5], 0x8000
	v_lshl_add_u64 v[210:211], v[210:211], 0, s[4:5]
	v_add_u32_e32 v226, 0x100, v226
	v_add_u32_e32 v227, 0x400, v227
	s_and_b64 vcc, exec, s[2:3]
	s_cbranch_vccnz .LBB0_335

.LBB0_713:
	s_waitcnt vmcnt(0)
	v_and_b32_e32 v2, 64, v218
	v_xor_b32_e32 v0, 32, v218
	v_add_u32_e32 v2, 64, v2
	v_cmp_lt_i32_e32 vcc, v0, v2
	s_waitcnt vmcnt(0)
	s_barrier
	v_mov_b32_e32 v10, v64
	v_cndmask_b32_e32 v0, v218, v0, vcc
	v_lshlrev_b32_e32 v0, 2, v0
	ds_bpermute_b32 v0, v0, v180
	v_ashrrev_i32_e32 v145, 31, v144
	s_waitcnt lgkmcnt(0)
	v_add_f32_e32 v0, v180, v0
	v_div_scale_f32 v2, s[0:1], v0, v0, 1.0
	v_rcp_f32_e32 v3, v2
	s_mov_b64 s[0:1], 0x8000
	v_fma_f32 v4, -v2, v3, 1.0
	v_fmac_f32_e32 v3, v4, v3
	v_div_scale_f32 v4, vcc, 1.0, v0, 1.0
	v_mul_f32_e32 v5, v4, v3
	v_fma_f32 v6, -v2, v5, v4
	v_fmac_f32_e32 v5, v6, v3
	v_fma_f32 v2, -v2, v5, v4
	v_div_fmas_f32 v2, v2, v3, v5
	v_div_fixup_f32 v2, v2, v0, 1.0
	v_lshlrev_b32_e32 v0, 1, v178
	v_add_u32_e32 v6, s31, v177
	v_and_b32_e32 v12, 16, v0
	v_lshlrev_b32_e32 v0, 9, v179
	v_ashrrev_i32_e32 v7, 31, v6
	v_and_b32_e32 v80, 0x1c00, v0
	v_or_b32_e32 v0, v175, v156
	v_lshlrev_b64 v[6:7], 17, v[6:7]
	v_lshl_add_u64 v[6:7], s[70:71], 0, v[6:7]
	v_lshlrev_b32_e32 v0, 1, v0
	v_lshl_add_u64 v[8:9], v[6:7], 0, v[0:1]
	global_load_dwordx2 v[208:209], v[8:9], off
	global_load_dwordx2 v[210:211], v[8:9], off offset:16
	global_load_dwordx2 v[222:223], v[8:9], off offset:32
	global_load_dwordx2 v[224:225], v[8:9], off offset:48
	global_load_dwordx2 v[226:227], v[8:9], off offset:1024
	global_load_dwordx2 v[228:229], v[8:9], off offset:1040
	global_load_dwordx2 v[230:231], v[8:9], off offset:1056
	global_load_dwordx2 v[232:233], v[8:9], off offset:1072
	global_load_dwordx2 v[240:241], v[8:9], off offset:2048
	global_load_dwordx2 v[242:243], v[8:9], off offset:2064
	global_load_dwordx2 v[244:245], v[8:9], off offset:2080
	global_load_dwordx2 v[246:247], v[8:9], off offset:2096
	global_load_dwordx2 v[248:249], v[8:9], off offset:3072
	global_load_dwordx2 v[250:251], v[8:9], off offset:3088
	global_load_dwordx2 v[252:253], v[8:9], off offset:3104
	global_load_dwordx2 v[254:255], v[8:9], off offset:3120
	v_lshlrev_b64 v[4:5], 19, v[144:145]
	s_and_b64 vcc, exec, s[10:11]
	s_waitcnt vmcnt(15)
	v_mov_b32_e32 v8, v208
	v_mov_b32_e32 v9, v209
	v_lshlrev_b32_e32 v3, 16, v8
	v_mul_f32_e32 v0, 0xbfb8aa3b, v3
	v_exp_f32_e32 v0, v0
	s_nop 0
	v_add_f32_e32 v0, 1.0, v0
	v_rcp_f32_e32 v11, v0
	s_nop 0
	v_pk_mul_f32 v[10:11], v[10:11], v[2:3]
	v_and_b32_e32 v3, 0xffff0000, v8
	v_mul_f32_e32 v8, 0xbfb8aa3b, v3
	v_exp_f32_e32 v8, v8
	v_mul_f32_e32 v0, v10, v11
	v_mov_b32_e32 v10, v65
	v_add_f32_e32 v8, 1.0, v8
	v_rcp_f32_e32 v11, v8
	s_nop 0
	v_pk_mul_f32 v[10:11], v[10:11], v[2:3]
	v_lshlrev_b32_e32 v3, 16, v9
	v_mul_f32_e32 v8, 0xbfb8aa3b, v3
	v_exp_f32_e32 v8, v8
	v_mul_f32_e32 v13, v10, v11
	v_mov_b32_e32 v10, v66
	v_add_f32_e32 v8, 1.0, v8
	v_rcp_f32_e32 v11, v8
	s_nop 0
	v_pk_mul_f32 v[10:11], v[10:11], v[2:3]
	v_and_b32_e32 v3, 0xffff0000, v9
	v_mul_f32_e32 v8, 0xbfb8aa3b, v3
	v_exp_f32_e32 v8, v8
	v_mul_f32_e32 v11, v10, v11
	v_cvt_pk_bf16_f32 v10, v0, v13
	v_or_b32_e32 v13, v12, v176
	v_add_f32_e32 v8, 1.0, v8
	v_rcp_f32_e32 v9, v8
	v_mov_b32_e32 v8, v67
	v_or_b32_e32 v81, v13, v156
	v_or_b32_e32 v0, v81, v80
	v_pk_mul_f32 v[8:9], v[8:9], v[2:3]
	v_lshlrev_b32_e32 v0, 1, v0
	v_mul_f32_e32 v3, v8, v9
	v_lshl_add_u64 v[8:9], s[8:9], 0, v[4:5]
	v_lshl_add_u64 v[14:15], v[8:9], 0, v[0:1]
	v_add_lshl_u32 v4, v175, v156, 1
	v_mov_b32_e32 v5, v1
	v_cvt_pk_bf16_f32 v11, v11, v3
	global_store_dwordx2 v[14:15], v[10:11], off
	v_lshl_add_u64 v[4:5], v[6:7], 0, v[4:5]
	v_or_b32_e32 v82, v13, v171
	s_waitcnt vmcnt(15)
	v_mov_b32_e32 v10, v210
	v_mov_b32_e32 v11, v211
	v_lshlrev_b32_e32 v3, 16, v10
	v_mul_f32_e32 v64, 0xbfb8aa3b, v3
	v_exp_f32_e32 v64, v64
	s_nop 0
	v_add_f32_e32 v64, 1.0, v64
	v_rcp_f32_e32 v65, v64
	v_mov_b32_e32 v64, v68
	v_or_b32_e32 v68, v82, v80
	v_pk_mul_f32 v[64:65], v[64:65], v[2:3]
	v_and_b32_e32 v3, 0xffff0000, v10
	v_mul_f32_e32 v10, 0xbfb8aa3b, v3
	v_exp_f32_e32 v10, v10
	v_mul_f32_e32 v66, v64, v65
	v_mov_b32_e32 v64, v69
	v_bitop3_b32 v69, v176, v12, v172 bitop3:0x36
	v_add_f32_e32 v10, 1.0, v10
	v_rcp_f32_e32 v65, v10
	s_nop 0
	v_pk_mul_f32 v[64:65], v[64:65], v[2:3]
	v_lshlrev_b32_e32 v3, 16, v11
	v_mul_f32_e32 v10, 0xbfb8aa3b, v3
	v_exp_f32_e32 v10, v10
	v_mul_f32_e32 v67, v64, v65
	v_mov_b32_e32 v64, v70
	v_mov_b32_e32 v70, v76
	v_add_f32_e32 v10, 1.0, v10
	v_rcp_f32_e32 v65, v10
	s_nop 0
	v_pk_mul_f32 v[64:65], v[64:65], v[2:3]
	v_and_b32_e32 v3, 0xffff0000, v11
	v_mul_f32_e32 v10, 0xbfb8aa3b, v3
	v_exp_f32_e32 v10, v10
	v_mul_f32_e32 v64, v64, v65
	v_add_f32_e32 v10, 1.0, v10
	v_rcp_f32_e32 v11, v10
	v_mov_b32_e32 v10, v71
	v_pk_mul_f32 v[10:11], v[10:11], v[2:3]
	s_nop 0
	v_mul_f32_e32 v3, v10, v11
	v_cvt_pk_bf16_f32 v10, v66, v67
	v_cvt_pk_bf16_f32 v11, v64, v3
	global_store_dwordx2 v[14:15], v[10:11], off offset:16
	v_mov_b32_e32 v64, v72
	s_waitcnt vmcnt(15)
	v_mov_b32_e32 v10, v222
	v_mov_b32_e32 v11, v223
	v_lshlrev_b32_e32 v3, 16, v10
	v_mul_f32_e32 v13, 0xbfb8aa3b, v3
	v_exp_f32_e32 v13, v13
	s_nop 0
	v_add_f32_e32 v13, 1.0, v13
	v_rcp_f32_e32 v65, v13
	s_nop 0
	v_pk_mul_f32 v[64:65], v[64:65], v[2:3]
	v_and_b32_e32 v3, 0xffff0000, v10
	v_mul_f32_e32 v10, 0xbfb8aa3b, v3
	v_exp_f32_e32 v10, v10
	v_mul_f32_e32 v13, v64, v65
	v_mov_b32_e32 v64, v73
	v_add_f32_e32 v10, 1.0, v10
	v_rcp_f32_e32 v65, v10
	s_nop 0
	v_pk_mul_f32 v[64:65], v[64:65], v[2:3]
	v_lshlrev_b32_e32 v3, 16, v11
	v_mul_f32_e32 v10, 0xbfb8aa3b, v3
	v_exp_f32_e32 v10, v10
	v_mul_f32_e32 v66, v64, v65
	v_mov_b32_e32 v64, v74
	v_cvt_pk_bf16_f32 v66, v13, v66
	v_add_f32_e32 v10, 1.0, v10
	v_rcp_f32_e32 v65, v10
	s_nop 0
	v_pk_mul_f32 v[64:65], v[64:65], v[2:3]
	v_and_b32_e32 v3, 0xffff0000, v11
	v_mul_f32_e32 v10, 0xbfb8aa3b, v3
	v_exp_f32_e32 v10, v10
	v_mul_f32_e32 v64, v64, v65
	v_add_f32_e32 v10, 1.0, v10
	v_rcp_f32_e32 v11, v10
	v_mov_b32_e32 v10, v75
	v_pk_mul_f32 v[10:11], v[10:11], v[2:3]
	s_nop 0
	v_mul_f32_e32 v3, v10, v11
	v_cvt_pk_bf16_f32 v67, v64, v3
	v_or_b32_e32 v3, v69, v80
	v_lshlrev_b32_e32 v10, 1, v3
	v_mov_b32_e32 v11, v1
	v_lshl_add_u64 v[64:65], v[8:9], 0, v[10:11]
	global_store_dwordx2 v[64:65], v[66:67], off
	s_waitcnt vmcnt(15)
	v_mov_b32_e32 v66, v224
	v_mov_b32_e32 v67, v225
	v_lshlrev_b32_e32 v3, 16, v66
	v_mul_f32_e32 v13, 0xbfb8aa3b, v3
	v_exp_f32_e32 v13, v13
	s_nop 0
	v_add_f32_e32 v13, 1.0, v13
	v_rcp_f32_e32 v71, v13
	s_nop 0
	v_pk_mul_f32 v[70:71], v[70:71], v[2:3]
	v_and_b32_e32 v3, 0xffff0000, v66
	v_mul_f32_e32 v66, 0xbfb8aa3b, v3
	v_exp_f32_e32 v66, v66
	v_mul_f32_e32 v13, v70, v71
	v_mov_b32_e32 v70, v77
	v_add_f32_e32 v66, 1.0, v66
	v_rcp_f32_e32 v71, v66
	s_nop 0
	v_pk_mul_f32 v[70:71], v[70:71], v[2:3]
	v_lshlrev_b32_e32 v3, 16, v67
	v_mul_f32_e32 v66, 0xbfb8aa3b, v3
	v_exp_f32_e32 v66, v66
	v_mul_f32_e32 v72, v70, v71
	v_mov_b32_e32 v70, v78
	v_cvt_pk_bf16_f32 v72, v13, v72
	v_add_f32_e32 v66, 1.0, v66
	v_rcp_f32_e32 v71, v66
	v_mov_b32_e32 v13, v1
	v_pk_mul_f32 v[70:71], v[70:71], v[2:3]
	v_and_b32_e32 v3, 0xffff0000, v67
	v_mul_f32_e32 v66, 0xbfb8aa3b, v3
	v_exp_f32_e32 v66, v66
	v_mul_f32_e32 v70, v70, v71
	v_or_b32_e32 v71, 0x200, v80
	v_add_f32_e32 v66, 1.0, v66
	v_rcp_f32_e32 v67, v66
	v_mov_b32_e32 v66, v79
	v_pk_mul_f32 v[66:67], v[66:67], v[2:3]
	s_nop 0
	v_mul_f32_e32 v3, v66, v67
	v_cvt_pk_bf16_f32 v73, v70, v3
	v_bitop3_b32 v70, v176, v12, v173 bitop3:0x36
	v_or_b32_e32 v3, v70, v80
	v_lshlrev_b32_e32 v12, 1, v3
	v_lshl_add_u64 v[66:67], v[8:9], 0, v[12:13]
	global_store_dwordx2 v[66:67], v[72:73], off
	s_waitcnt vmcnt(15)
	v_mov_b32_e32 v72, v226
	v_mov_b32_e32 v73, v227
	v_lshlrev_b32_e32 v3, 16, v72
	v_mul_f32_e32 v74, 0xbfb8aa3b, v3
	v_exp_f32_e32 v74, v74
	s_nop 0
	v_add_f32_e32 v74, 1.0, v74
	v_rcp_f32_e32 v75, v74
	v_mov_b32_e32 v74, v48
	v_pk_mul_f32 v[74:75], v[74:75], v[2:3]
	v_and_b32_e32 v3, 0xffff0000, v72
	v_mul_f32_e32 v48, 0xbfb8aa3b, v3
	v_exp_f32_e32 v48, v48
	v_mul_f32_e32 v76, v74, v75
	v_mov_b32_e32 v74, v49
	v_add_f32_e32 v48, 1.0, v48
	v_rcp_f32_e32 v75, v48
	s_nop 0
	v_pk_mul_f32 v[48:49], v[74:75], v[2:3]
	v_lshlrev_b32_e32 v3, 16, v73
	v_mul_f32_e32 v72, v48, v49
	v_mul_f32_e32 v48, 0xbfb8aa3b, v3
	v_exp_f32_e32 v48, v48
	s_nop 0
	v_add_f32_e32 v48, 1.0, v48
	v_rcp_f32_e32 v49, v48
	v_mov_b32_e32 v48, v50
	v_pk_mul_f32 v[48:49], v[48:49], v[2:3]
	v_and_b32_e32 v3, 0xffff0000, v73
	v_mul_f32_e32 v50, v48, v49
	v_mul_f32_e32 v48, 0xbfb8aa3b, v3
	v_exp_f32_e32 v48, v48
	s_nop 0
	v_add_f32_e32 v48, 1.0, v48
	v_rcp_f32_e32 v49, v48
	v_mov_b32_e32 v48, v51
	v_pk_mul_f32 v[48:49], v[48:49], v[2:3]
	s_nop 0
	v_mul_f32_e32 v3, v48, v49
	v_cvt_pk_bf16_f32 v48, v76, v72
	v_cvt_pk_bf16_f32 v49, v50, v3
	global_store_dwordx2 v[14:15], v[48:49], off offset:1024
	v_add_lshl_u32 v14, v175, v171, 1
	v_mov_b32_e32 v15, v1
	v_lshl_add_u64 v[14:15], v[6:7], 0, v[14:15]
	v_or_b32_e32 v72, v81, v71
	s_waitcnt vmcnt(15)
	v_mov_b32_e32 v48, v228
	v_mov_b32_e32 v49, v229
	v_lshlrev_b32_e32 v3, 16, v48
	v_mul_f32_e32 v50, 0xbfb8aa3b, v3
	v_exp_f32_e32 v50, v50
	s_nop 0
	v_add_f32_e32 v50, 1.0, v50
	v_rcp_f32_e32 v51, v50
	v_mov_b32_e32 v50, v52
	v_pk_mul_f32 v[50:51], v[50:51], v[2:3]
	v_and_b32_e32 v3, 0xffff0000, v48
	v_mul_f32_e32 v48, 0xbfb8aa3b, v3
	v_exp_f32_e32 v48, v48
	v_mul_f32_e32 v52, v50, v51
	v_mov_b32_e32 v50, v53
	v_add_f32_e32 v48, 1.0, v48
	v_rcp_f32_e32 v51, v48
	s_nop 0
	v_pk_mul_f32 v[50:51], v[50:51], v[2:3]
	v_lshlrev_b32_e32 v3, 16, v49
	v_mul_f32_e32 v48, 0xbfb8aa3b, v3
	v_exp_f32_e32 v48, v48
	v_mul_f32_e32 v53, v50, v51
	v_mov_b32_e32 v50, v54
	v_add_f32_e32 v48, 1.0, v48
	v_rcp_f32_e32 v51, v48
	s_nop 0
	v_pk_mul_f32 v[50:51], v[50:51], v[2:3]
	v_and_b32_e32 v3, 0xffff0000, v49
	v_mul_f32_e32 v48, 0xbfb8aa3b, v3
	v_exp_f32_e32 v48, v48
	v_mul_f32_e32 v50, v50, v51
	v_mov_b32_e32 v51, v1
	v_add_f32_e32 v48, 1.0, v48
	v_rcp_f32_e32 v49, v48
	v_mov_b32_e32 v48, v55
	v_pk_mul_f32 v[48:49], v[48:49], v[2:3]
	s_nop 0
	v_mul_f32_e32 v3, v48, v49
	v_cvt_pk_bf16_f32 v49, v50, v3
	v_lshlrev_b32_e32 v50, 1, v72
	v_cvt_pk_bf16_f32 v48, v52, v53
	v_lshl_add_u64 v[54:55], v[8:9], 0, v[50:51]
	global_store_dwordx2 v[54:55], v[48:49], off offset:16
	v_add_lshl_u32 v48, v175, v172, 1
	v_mov_b32_e32 v49, v1
	v_lshl_add_u64 v[48:49], v[6:7], 0, v[48:49]
	v_mov_b32_e32 v72, v56
	v_lshl_add_u64 v[8:9], v[8:9], 0, s[0:1]
	v_lshl_add_u64 v[10:11], v[8:9], 0, v[10:11]
	v_lshl_add_u64 v[12:13], v[8:9], 0, v[12:13]
	v_or_b32_e32 v52, v82, v71
	s_mov_b64 s[0:1], 0
	s_waitcnt vmcnt(15)
	v_mov_b32_e32 v54, v230
	v_mov_b32_e32 v55, v231
	v_lshlrev_b32_e32 v3, 16, v54
	v_mul_f32_e32 v53, 0xbfb8aa3b, v3
	v_exp_f32_e32 v53, v53
	s_nop 0
	v_add_f32_e32 v53, 1.0, v53
	v_rcp_f32_e32 v73, v53
	s_nop 0
	v_pk_mul_f32 v[72:73], v[72:73], v[2:3]
	v_and_b32_e32 v3, 0xffff0000, v54
	v_mul_f32_e32 v54, 0xbfb8aa3b, v3
	v_exp_f32_e32 v54, v54
	v_mul_f32_e32 v53, v72, v73
	v_mov_b32_e32 v72, v57
	v_add_f32_e32 v54, 1.0, v54
	v_rcp_f32_e32 v73, v54
	s_nop 0
	v_pk_mul_f32 v[56:57], v[72:73], v[2:3]
	v_lshlrev_b32_e32 v3, 16, v55
	v_mul_f32_e32 v54, 0xbfb8aa3b, v3
	v_exp_f32_e32 v54, v54
	v_mul_f32_e32 v72, v56, v57
	v_mov_b32_e32 v56, v58
	v_add_f32_e32 v54, 1.0, v54
	v_rcp_f32_e32 v57, v54
	s_nop 0
	v_pk_mul_f32 v[56:57], v[56:57], v[2:3]
	v_and_b32_e32 v3, 0xffff0000, v55
	v_mul_f32_e32 v54, 0xbfb8aa3b, v3
	v_exp_f32_e32 v54, v54
	v_mul_f32_e32 v56, v56, v57
	v_add_f32_e32 v54, 1.0, v54
	v_rcp_f32_e32 v55, v54
	v_mov_b32_e32 v54, v59
	v_pk_mul_f32 v[54:55], v[54:55], v[2:3]
	s_nop 0
	v_mul_f32_e32 v3, v54, v55
	v_cvt_pk_bf16_f32 v54, v53, v72
	v_cvt_pk_bf16_f32 v55, v56, v3
	global_store_dwordx2 v[64:65], v[54:55], off offset:1024
	v_add_lshl_u32 v54, v175, v173, 1
	v_mov_b32_e32 v55, v1
	v_lshl_add_u64 v[6:7], v[6:7], 0, v[54:55]
	v_or_b32_e32 v53, v69, v71
	s_waitcnt vmcnt(15)
	v_mov_b32_e32 v54, v232
	v_mov_b32_e32 v55, v233
	v_lshlrev_b32_e32 v3, 16, v54
	v_mul_f32_e32 v56, 0xbfb8aa3b, v3
	v_exp_f32_e32 v56, v56
	s_nop 0
	v_add_f32_e32 v56, 1.0, v56
	v_rcp_f32_e32 v57, v56
	v_mov_b32_e32 v56, v60
	v_pk_mul_f32 v[56:57], v[56:57], v[2:3]
	v_and_b32_e32 v3, 0xffff0000, v54
	v_mul_f32_e32 v54, 0xbfb8aa3b, v3
	v_exp_f32_e32 v54, v54
	v_mul_f32_e32 v58, v56, v57
	v_mov_b32_e32 v56, v61
	v_add_f32_e32 v54, 1.0, v54
	v_rcp_f32_e32 v57, v54
	s_nop 0
	v_pk_mul_f32 v[56:57], v[56:57], v[2:3]
	v_lshlrev_b32_e32 v3, 16, v55
	v_mul_f32_e32 v54, 0xbfb8aa3b, v3
	v_exp_f32_e32 v54, v54
	v_mul_f32_e32 v59, v56, v57
	v_mov_b32_e32 v56, v62
	v_add_f32_e32 v54, 1.0, v54
	v_rcp_f32_e32 v57, v54
	s_nop 0
	v_pk_mul_f32 v[56:57], v[56:57], v[2:3]
	v_and_b32_e32 v3, 0xffff0000, v55
	v_mul_f32_e32 v54, 0xbfb8aa3b, v3
	v_exp_f32_e32 v54, v54
	v_mul_f32_e32 v57, v56, v57
	v_cvt_pk_bf16_f32 v56, v58, v59
	v_mov_b32_e32 v58, v32
	v_add_f32_e32 v54, 1.0, v54
	v_rcp_f32_e32 v55, v54
	v_mov_b32_e32 v54, v63
	v_pk_mul_f32 v[54:55], v[54:55], v[2:3]
	s_nop 0
	v_mul_f32_e32 v3, v54, v55
	v_cvt_pk_bf16_f32 v57, v57, v3
	global_store_dwordx2 v[66:67], v[56:57], off offset:1024
	v_or_b32_e32 v54, v70, v71
	s_waitcnt vmcnt(15)
	v_mov_b32_e32 v56, v240
	v_mov_b32_e32 v57, v241
	v_lshlrev_b32_e32 v3, 16, v56
	v_mul_f32_e32 v55, 0xbfb8aa3b, v3
	v_exp_f32_e32 v55, v55
	s_nop 0
	v_add_f32_e32 v55, 1.0, v55
	v_rcp_f32_e32 v59, v55
	s_nop 0
	v_pk_mul_f32 v[58:59], v[58:59], v[2:3]
	v_and_b32_e32 v3, 0xffff0000, v56
	v_mul_f32_e32 v32, 0xbfb8aa3b, v3
	v_exp_f32_e32 v32, v32
	v_mul_f32_e32 v55, v58, v59
	v_mov_b32_e32 v58, v33
	v_add_f32_e32 v32, 1.0, v32
	v_rcp_f32_e32 v59, v32
	s_nop 0
	v_pk_mul_f32 v[32:33], v[58:59], v[2:3]
	v_lshlrev_b32_e32 v3, 16, v57
	v_mul_f32_e32 v56, v32, v33
	v_mul_f32_e32 v32, 0xbfb8aa3b, v3
	v_exp_f32_e32 v32, v32
	s_nop 0
	v_add_f32_e32 v32, 1.0, v32
	v_rcp_f32_e32 v33, v32
	v_mov_b32_e32 v32, v34
	v_pk_mul_f32 v[32:33], v[32:33], v[2:3]
	v_and_b32_e32 v3, 0xffff0000, v57
	v_mul_f32_e32 v34, v32, v33
	v_mul_f32_e32 v32, 0xbfb8aa3b, v3
	v_exp_f32_e32 v32, v32
	s_nop 0
	v_add_f32_e32 v32, 1.0, v32
	v_rcp_f32_e32 v33, v32
	v_mov_b32_e32 v32, v35
	v_pk_mul_f32 v[32:33], v[32:33], v[2:3]
	s_nop 0
	v_mul_f32_e32 v3, v32, v33
	v_cvt_pk_bf16_f32 v33, v34, v3
	v_lshl_add_u64 v[34:35], v[8:9], 0, v[0:1]
	v_cvt_pk_bf16_f32 v32, v55, v56
	global_store_dwordx2 v[34:35], v[32:33], off
	v_mov_b32_e32 v34, v36
	s_waitcnt vmcnt(15)
	v_mov_b32_e32 v32, v242
	v_mov_b32_e32 v33, v243
	v_lshlrev_b32_e32 v3, 16, v32
	v_mul_f32_e32 v0, 0xbfb8aa3b, v3
	v_exp_f32_e32 v0, v0
	s_nop 0
	v_add_f32_e32 v0, 1.0, v0
	v_rcp_f32_e32 v35, v0
	s_nop 0
	v_pk_mul_f32 v[34:35], v[34:35], v[2:3]
	v_and_b32_e32 v3, 0xffff0000, v32
	v_mul_f32_e32 v32, 0xbfb8aa3b, v3
	v_exp_f32_e32 v32, v32
	v_mul_f32_e32 v0, v34, v35
	v_mov_b32_e32 v34, v37
	v_add_f32_e32 v32, 1.0, v32
	v_rcp_f32_e32 v35, v32
	s_nop 0
	v_pk_mul_f32 v[34:35], v[34:35], v[2:3]
	v_lshlrev_b32_e32 v3, 16, v33
	v_mul_f32_e32 v32, 0xbfb8aa3b, v3
	v_exp_f32_e32 v32, v32
	v_mul_f32_e32 v36, v34, v35
	v_mov_b32_e32 v34, v38
	v_add_f32_e32 v32, 1.0, v32
	v_rcp_f32_e32 v35, v32
	s_nop 0
	v_pk_mul_f32 v[34:35], v[34:35], v[2:3]
	v_and_b32_e32 v3, 0xffff0000, v33
	v_mul_f32_e32 v32, 0xbfb8aa3b, v3
	v_exp_f32_e32 v32, v32
	v_mul_f32_e32 v34, v34, v35
	v_add_f32_e32 v32, 1.0, v32
	v_rcp_f32_e32 v33, v32
	v_mov_b32_e32 v32, v39
	v_pk_mul_f32 v[32:33], v[32:33], v[2:3]
	s_nop 0
	v_mul_f32_e32 v3, v32, v33
	v_cvt_pk_bf16_f32 v32, v0, v36
	v_lshlrev_b32_e32 v0, 1, v68
	v_cvt_pk_bf16_f32 v33, v34, v3
	v_lshl_add_u64 v[34:35], v[8:9], 0, v[0:1]
	global_store_dwordx2 v[34:35], v[32:33], off
	v_mov_b32_e32 v34, v40
	s_waitcnt vmcnt(15)
	v_mov_b32_e32 v32, v244
	v_mov_b32_e32 v33, v245
	v_lshlrev_b32_e32 v3, 16, v32
	v_mul_f32_e32 v0, 0xbfb8aa3b, v3
	v_exp_f32_e32 v0, v0
	s_nop 0
	v_add_f32_e32 v0, 1.0, v0
	v_rcp_f32_e32 v35, v0
	s_nop 0
	v_pk_mul_f32 v[34:35], v[34:35], v[2:3]
	v_and_b32_e32 v3, 0xffff0000, v32
	v_mul_f32_e32 v32, 0xbfb8aa3b, v3
	v_exp_f32_e32 v32, v32
	v_mul_f32_e32 v0, v34, v35
	v_mov_b32_e32 v34, v41
	v_add_f32_e32 v32, 1.0, v32
	v_rcp_f32_e32 v35, v32
	s_nop 0
	v_pk_mul_f32 v[34:35], v[34:35], v[2:3]
	v_lshlrev_b32_e32 v3, 16, v33
	v_mul_f32_e32 v32, 0xbfb8aa3b, v3
	v_exp_f32_e32 v32, v32
	v_mul_f32_e32 v36, v34, v35
	v_mov_b32_e32 v34, v42
	v_add_f32_e32 v32, 1.0, v32
	v_rcp_f32_e32 v35, v32
	s_nop 0
	v_pk_mul_f32 v[34:35], v[34:35], v[2:3]
	v_and_b32_e32 v3, 0xffff0000, v33
	v_mul_f32_e32 v32, 0xbfb8aa3b, v3
	v_exp_f32_e32 v32, v32
	v_mul_f32_e32 v34, v34, v35
	v_add_f32_e32 v32, 1.0, v32
	v_rcp_f32_e32 v33, v32
	v_mov_b32_e32 v32, v43
	v_pk_mul_f32 v[32:33], v[32:33], v[2:3]
	s_nop 0
	v_mul_f32_e32 v3, v32, v33
	v_cvt_pk_bf16_f32 v32, v0, v36
	v_cvt_pk_bf16_f32 v33, v34, v3
	global_store_dwordx2 v[10:11], v[32:33], off
	v_mov_b32_e32 v32, v44
	s_waitcnt vmcnt(15)
	v_mov_b32_e32 v10, v246
	v_mov_b32_e32 v11, v247
	v_lshlrev_b32_e32 v3, 16, v10
	v_mul_f32_e32 v0, 0xbfb8aa3b, v3
	v_exp_f32_e32 v0, v0
	s_nop 0
	v_add_f32_e32 v0, 1.0, v0
	v_rcp_f32_e32 v33, v0
	s_nop 0
	v_pk_mul_f32 v[32:33], v[32:33], v[2:3]
	v_and_b32_e32 v3, 0xffff0000, v10
	v_mul_f32_e32 v10, 0xbfb8aa3b, v3
	v_exp_f32_e32 v10, v10
	v_mul_f32_e32 v0, v32, v33
	v_mov_b32_e32 v32, v45
	v_add_f32_e32 v10, 1.0, v10
	v_rcp_f32_e32 v33, v10
	s_nop 0
	v_pk_mul_f32 v[32:33], v[32:33], v[2:3]
	v_lshlrev_b32_e32 v3, 16, v11
	v_mul_f32_e32 v10, 0xbfb8aa3b, v3
	v_exp_f32_e32 v10, v10
	v_mul_f32_e32 v34, v32, v33
	v_mov_b32_e32 v32, v46
	v_add_f32_e32 v10, 1.0, v10
	v_rcp_f32_e32 v33, v10
	s_nop 0
	v_pk_mul_f32 v[32:33], v[32:33], v[2:3]
	v_and_b32_e32 v3, 0xffff0000, v11
	v_mul_f32_e32 v10, 0xbfb8aa3b, v3
	v_exp_f32_e32 v10, v10
	v_mul_f32_e32 v32, v32, v33
	v_add_f32_e32 v10, 1.0, v10
	v_rcp_f32_e32 v11, v10
	v_mov_b32_e32 v10, v47
	v_pk_mul_f32 v[10:11], v[10:11], v[2:3]
	s_nop 0
	v_mul_f32_e32 v3, v10, v11
	v_cvt_pk_bf16_f32 v10, v0, v34
	v_cvt_pk_bf16_f32 v11, v32, v3
	global_store_dwordx2 v[12:13], v[10:11], off
	v_mov_b32_e32 v10, v16
	s_waitcnt vmcnt(15)
	v_mov_b32_e32 v4, v248
	v_mov_b32_e32 v5, v249
	v_lshlrev_b32_e32 v3, 16, v4
	v_mul_f32_e32 v0, 0xbfb8aa3b, v3
	v_exp_f32_e32 v0, v0
	s_nop 0
	v_add_f32_e32 v0, 1.0, v0
	v_rcp_f32_e32 v11, v0
	s_nop 0
	v_pk_mul_f32 v[10:11], v[10:11], v[2:3]
	v_and_b32_e32 v3, 0xffff0000, v4
	v_mul_f32_e32 v4, 0xbfb8aa3b, v3
	v_exp_f32_e32 v4, v4
	v_mul_f32_e32 v0, v10, v11
	v_mov_b32_e32 v10, v17
	v_add_f32_e32 v4, 1.0, v4
	v_rcp_f32_e32 v11, v4
	s_nop 0
	v_pk_mul_f32 v[10:11], v[10:11], v[2:3]
	v_lshlrev_b32_e32 v3, 16, v5
	v_mul_f32_e32 v4, 0xbfb8aa3b, v3
	v_exp_f32_e32 v4, v4
	v_mul_f32_e32 v12, v10, v11
	v_mov_b32_e32 v10, v18
	v_add_f32_e32 v4, 1.0, v4
	v_rcp_f32_e32 v11, v4
	s_nop 0
	v_pk_mul_f32 v[10:11], v[10:11], v[2:3]
	v_and_b32_e32 v3, 0xffff0000, v5
	v_mul_f32_e32 v4, 0xbfb8aa3b, v3
	v_exp_f32_e32 v4, v4
	v_mul_f32_e32 v10, v10, v11
	v_add_f32_e32 v4, 1.0, v4
	v_rcp_f32_e32 v5, v4
	v_mov_b32_e32 v4, v19
	v_pk_mul_f32 v[4:5], v[4:5], v[2:3]
	s_nop 0
	v_mul_f32_e32 v3, v4, v5
	v_cvt_pk_bf16_f32 v5, v10, v3
	v_lshl_add_u64 v[10:11], v[8:9], 0, v[50:51]
	v_cvt_pk_bf16_f32 v4, v0, v12
	global_store_dwordx2 v[10:11], v[4:5], off
	v_mov_b32_e32 v10, v20
	s_waitcnt vmcnt(15)
	v_mov_b32_e32 v4, v250
	v_mov_b32_e32 v5, v251
	v_lshlrev_b32_e32 v3, 16, v4
	v_mul_f32_e32 v0, 0xbfb8aa3b, v3
	v_exp_f32_e32 v0, v0
	s_nop 0
	v_add_f32_e32 v0, 1.0, v0
	v_rcp_f32_e32 v11, v0
	s_nop 0
	v_pk_mul_f32 v[10:11], v[10:11], v[2:3]
	v_and_b32_e32 v3, 0xffff0000, v4
	v_mul_f32_e32 v4, 0xbfb8aa3b, v3
	v_exp_f32_e32 v4, v4
	v_mul_f32_e32 v0, v10, v11
	v_mov_b32_e32 v10, v21
	v_add_f32_e32 v4, 1.0, v4
	v_rcp_f32_e32 v11, v4
	s_nop 0
	v_pk_mul_f32 v[10:11], v[10:11], v[2:3]
	v_lshlrev_b32_e32 v3, 16, v5
	v_mul_f32_e32 v4, 0xbfb8aa3b, v3
	v_exp_f32_e32 v4, v4
	v_mul_f32_e32 v12, v10, v11
	v_mov_b32_e32 v10, v22
	v_add_f32_e32 v4, 1.0, v4
	v_rcp_f32_e32 v11, v4
	s_nop 0
	v_pk_mul_f32 v[10:11], v[10:11], v[2:3]
	v_and_b32_e32 v3, 0xffff0000, v5
	v_mul_f32_e32 v4, 0xbfb8aa3b, v3
	v_exp_f32_e32 v4, v4
	v_mul_f32_e32 v10, v10, v11
	v_add_f32_e32 v4, 1.0, v4
	v_rcp_f32_e32 v5, v4
	v_mov_b32_e32 v4, v23
	v_pk_mul_f32 v[4:5], v[4:5], v[2:3]
	s_nop 0
	v_mul_f32_e32 v3, v4, v5
	v_cvt_pk_bf16_f32 v4, v0, v12
	v_lshlrev_b32_e32 v0, 1, v52
	v_cvt_pk_bf16_f32 v5, v10, v3
	v_lshl_add_u64 v[10:11], v[8:9], 0, v[0:1]
	global_store_dwordx2 v[10:11], v[4:5], off
	v_mov_b32_e32 v10, v24
	s_waitcnt vmcnt(15)
	v_mov_b32_e32 v4, v252
	v_mov_b32_e32 v5, v253
	v_lshlrev_b32_e32 v3, 16, v4
	v_mul_f32_e32 v0, 0xbfb8aa3b, v3
	v_exp_f32_e32 v0, v0
	s_nop 0
	v_add_f32_e32 v0, 1.0, v0
	v_rcp_f32_e32 v11, v0
	s_nop 0
	v_pk_mul_f32 v[10:11], v[10:11], v[2:3]
	v_and_b32_e32 v3, 0xffff0000, v4
	v_mul_f32_e32 v4, 0xbfb8aa3b, v3
	v_exp_f32_e32 v4, v4
	v_mul_f32_e32 v0, v10, v11
	v_mov_b32_e32 v10, v25
	v_add_f32_e32 v4, 1.0, v4
	v_rcp_f32_e32 v11, v4
	s_nop 0
	v_pk_mul_f32 v[10:11], v[10:11], v[2:3]
	v_lshlrev_b32_e32 v3, 16, v5
	v_mul_f32_e32 v4, 0xbfb8aa3b, v3
	v_exp_f32_e32 v4, v4
	v_mul_f32_e32 v12, v10, v11
	v_mov_b32_e32 v10, v26
	v_add_f32_e32 v4, 1.0, v4
	v_rcp_f32_e32 v11, v4
	s_nop 0
	v_pk_mul_f32 v[10:11], v[10:11], v[2:3]
	v_and_b32_e32 v3, 0xffff0000, v5
	v_mul_f32_e32 v4, 0xbfb8aa3b, v3
	v_exp_f32_e32 v4, v4
	v_mul_f32_e32 v10, v10, v11
	v_add_f32_e32 v4, 1.0, v4
	v_rcp_f32_e32 v5, v4
	v_mov_b32_e32 v4, v27
	v_pk_mul_f32 v[4:5], v[4:5], v[2:3]
	s_nop 0
	v_mul_f32_e32 v3, v4, v5
	v_cvt_pk_bf16_f32 v4, v0, v12
	v_lshlrev_b32_e32 v0, 1, v53
	v_cvt_pk_bf16_f32 v5, v10, v3
	v_lshl_add_u64 v[10:11], v[8:9], 0, v[0:1]
	global_store_dwordx2 v[10:11], v[4:5], off
	v_mov_b32_e32 v6, v28
	s_waitcnt vmcnt(15)
	v_mov_b32_e32 v4, v254
	v_mov_b32_e32 v5, v255
	v_lshlrev_b32_e32 v3, 16, v4
	v_mul_f32_e32 v0, 0xbfb8aa3b, v3
	v_exp_f32_e32 v0, v0
	s_nop 0
	v_add_f32_e32 v0, 1.0, v0
	v_rcp_f32_e32 v7, v0
	s_nop 0
	v_pk_mul_f32 v[6:7], v[6:7], v[2:3]
	v_and_b32_e32 v3, 0xffff0000, v4
	v_mul_f32_e32 v4, 0xbfb8aa3b, v3
	v_exp_f32_e32 v4, v4
	v_mul_f32_e32 v0, v6, v7
	v_mov_b32_e32 v6, v29
	v_add_f32_e32 v4, 1.0, v4
	v_rcp_f32_e32 v7, v4
	s_nop 0
	v_pk_mul_f32 v[6:7], v[6:7], v[2:3]
	v_lshlrev_b32_e32 v3, 16, v5
	v_mul_f32_e32 v4, 0xbfb8aa3b, v3
	v_exp_f32_e32 v4, v4
	v_mul_f32_e32 v10, v6, v7
	v_mov_b32_e32 v6, v30
	v_add_f32_e32 v4, 1.0, v4
	v_rcp_f32_e32 v7, v4
	s_nop 0
	v_pk_mul_f32 v[6:7], v[6:7], v[2:3]
	v_and_b32_e32 v3, 0xffff0000, v5
	v_mul_f32_e32 v4, 0xbfb8aa3b, v3
	v_exp_f32_e32 v4, v4
	v_mul_f32_e32 v6, v6, v7
	v_add_f32_e32 v4, 1.0, v4
	v_rcp_f32_e32 v5, v4
	v_mov_b32_e32 v4, v31
	v_pk_mul_f32 v[2:3], v[4:5], v[2:3]
	s_nop 0
	v_mul_f32_e32 v3, v2, v3
	v_cvt_pk_bf16_f32 v2, v0, v10
	v_lshlrev_b32_e32 v0, 1, v54
	v_lshl_add_u64 v[4:5], v[8:9], 0, v[0:1]
	v_cvt_pk_bf16_f32 v3, v6, v3
	global_store_dwordx2 v[4:5], v[2:3], off
	s_cbranch_vccnz .LBB0_709

.LBB0_717:
	s_add_i32 s0, s41, 2
	s_min_u32 s72, s0, s36
	s_cmp_gt_i32 s40, 0
	s_cselect_b32 s0, -1, 2
	s_add_i32 s42, s0, s40
	s_lshl_b64 s[0:1], s[72:73], 7
	s_add_u32 s0, s6, s0
	v_mov_b32_e32 v6, v152
	s_addc_u32 s1, s7, s1
	s_lshl_b32 s43, s72, 6
	v_ashrrev_i32_e32 v7, 4, v6
	s_add_i32 s43, s43, s25
	v_add_u32_e32 v0, s14, v7
	v_xor_b32_e32 v9, v0, v6
	v_add_u32_e32 v10, s43, v0
	v_lshlrev_b32_e32 v11, 3, v9
	v_lshrrev_b32_e32 v4, 8, v10
	v_mov_b32_e32 v12, s29
	v_lshrrev_b32_e32 v10, 3, v10
	v_lshlrev_b32_e32 v9, 7, v9
	v_mad_i32_i24 v4, v4, s33, v12
	v_and_or_b32 v10, v10, 30, s27
	v_and_b32_e32 v9, 0x600, v9
	v_lshlrev_b32_e32 v0, 5, v0
	v_ashrrev_i32_e32 v5, 31, v4
	v_lshl_or_b32 v9, v10, 11, v9
	v_and_b32_e32 v0, 0x1e0, v0
	v_and_b32_e32 v10, 24, v11
	v_or3_b32 v0, v9, v0, v10
	v_lshlrev_b64 v[4:5], 17, v[4:5]
	v_ashrrev_i32_e32 v8, 3, v6
	v_lshl_add_u64 v[4:5], s[70:71], 0, v[4:5]
	v_lshlrev_b32_e32 v0, 1, v0
	s_lshl_b32 s42, s42, 15
	v_lshl_add_u64 v[4:5], v[4:5], 0, v[0:1]
	v_add_u32_e32 v0, s15, v8
	s_add_i32 s42, s42, 0
	v_lshrrev_b32_e32 v9, 1, v0
	v_xor_b32_e32 v9, v9, v6
	s_add_i32 s44, s42, s16
	v_lshlrev_b32_e32 v0, 13, v0
	v_lshlrev_b32_e32 v9, 4, v9
	s_mov_b32 m0, s44
	v_and_or_b32 v0, v9, s28, v0
	global_load_lds_dwordx4 v[4:5], off
	s_add_i32 m0, s44, 0x4000
	s_add_i32 s42, s42, s20
	global_load_lds_dwordx4 v0, s[0:1]
	v_add_u32_e32 v0, s17, v7
	v_xor_b32_e32 v7, v0, v6
	v_add_u32_e32 v9, s43, v0
	v_lshlrev_b32_e32 v10, 3, v7
	v_lshrrev_b32_e32 v4, 8, v9
	v_lshrrev_b32_e32 v9, 3, v9
	v_lshlrev_b32_e32 v7, 7, v7
	v_mad_i32_i24 v4, v4, s33, v12
	v_and_or_b32 v9, v9, 30, s27
	v_and_b32_e32 v7, 0x600, v7
	v_lshlrev_b32_e32 v0, 5, v0
	v_ashrrev_i32_e32 v5, 31, v4
	v_lshl_or_b32 v7, v9, 11, v7
	v_and_b32_e32 v0, 0x1e0, v0
	v_and_b32_e32 v9, 24, v10
	v_or3_b32 v0, v7, v0, v9
	v_lshlrev_b64 v[4:5], 17, v[4:5]
	v_lshl_add_u64 v[4:5], s[70:71], 0, v[4:5]
	v_lshlrev_b32_e32 v0, 1, v0
	v_lshl_add_u64 v[4:5], v[4:5], 0, v[0:1]
	v_add_u32_e32 v0, s19, v8
	v_lshrrev_b32_e32 v7, 1, v0
	v_xor_b32_e32 v6, v7, v6
	v_lshlrev_b32_e32 v0, 13, v0
	v_lshlrev_b32_e32 v6, 4, v6
	s_mov_b32 m0, s42
	v_and_or_b32 v0, v6, s28, v0
	global_load_lds_dwordx4 v[4:5], off
	s_add_i32 m0, s42, 0x4000
	s_cmp_gt_i32 s41, s35
	global_load_lds_dwordx4 v0, s[0:1]
	s_cbranch_scc1 .LBB0_723
	s_lshl_b32 s0, s40, 15
	s_add_i32 s42, s0, 0
	v_add_u32_e32 v0, s42, v151
	v_add_u32_e32 v8, v0, v159
	v_add_u32_e32 v9, v0, v160
	v_add_u32_e32 v10, v0, v161
	v_add_u32_e32 v11, v0, v162
	v_add_u32_e32 v12, v0, v163
	v_add_u32_e32 v13, v0, v164
	v_add_u32_e32 v14, v0, v165
	v_add_u32_e32 v0, v0, v166
	s_cmpk_gt_i32 s37, 0x7f
	ds_read_b128 v[240:243], v8
	ds_read_b128 v[244:247], v9
	ds_read_b128 v[248:251], v10
	ds_read_b128 v[252:255], v11
	ds_read_b128 v[208:211], v12
	ds_read_b128 v[222:225], v13
	ds_read_b128 v[226:229], v14
	ds_read_b128 v[230:233], v0
	s_waitcnt lgkmcnt(7)
	v_mfma_f32_32x32x16_bf16 v[96:111], v[240:243], v[112:115], 0
	ds_read_b128 v[240:243], v8 offset:8192
	s_waitcnt lgkmcnt(7)
	v_mfma_f32_32x32x16_bf16 v[96:111], v[244:247], v[116:119], v[96:111]
	ds_read_b128 v[244:247], v9 offset:8192
	s_waitcnt lgkmcnt(7)
	v_mfma_f32_32x32x16_bf16 v[96:111], v[248:251], v[120:123], v[96:111]
	ds_read_b128 v[248:251], v10 offset:8192
	s_waitcnt lgkmcnt(7)
	v_mfma_f32_32x32x16_bf16 v[96:111], v[252:255], v[124:127], v[96:111]
	ds_read_b128 v[252:255], v11 offset:8192
	s_waitcnt lgkmcnt(7)
	v_mfma_f32_32x32x16_bf16 v[96:111], v[208:211], v[128:131], v[96:111]
	ds_read_b128 v[208:211], v12 offset:8192
	s_waitcnt lgkmcnt(7)
	v_mfma_f32_32x32x16_bf16 v[96:111], v[222:225], v[132:135], v[96:111]
	ds_read_b128 v[222:225], v13 offset:8192
	s_waitcnt lgkmcnt(7)
	v_mfma_f32_32x32x16_bf16 v[96:111], v[226:229], v[136:139], v[96:111]
	ds_read_b128 v[226:229], v14 offset:8192
	s_waitcnt lgkmcnt(7)
	v_mfma_f32_32x32x16_bf16 v[96:111], v[230:233], v[140:143], v[96:111]
	ds_read_b128 v[230:233], v0 offset:8192
	s_waitcnt lgkmcnt(7)
	v_mfma_f32_32x32x16_bf16 v[80:95], v[240:243], v[112:115], 0
	s_waitcnt lgkmcnt(6)
	v_mfma_f32_32x32x16_bf16 v[80:95], v[244:247], v[116:119], v[80:95]
	s_waitcnt lgkmcnt(5)
	v_mfma_f32_32x32x16_bf16 v[80:95], v[248:251], v[120:123], v[80:95]
	s_waitcnt lgkmcnt(4)
	v_mfma_f32_32x32x16_bf16 v[80:95], v[252:255], v[124:127], v[80:95]
	s_waitcnt lgkmcnt(3)
	v_mfma_f32_32x32x16_bf16 v[80:95], v[208:211], v[128:131], v[80:95]
	s_waitcnt lgkmcnt(2)
	v_mfma_f32_32x32x16_bf16 v[80:95], v[222:225], v[132:135], v[80:95]
	s_waitcnt lgkmcnt(1)
	v_mfma_f32_32x32x16_bf16 v[80:95], v[226:229], v[136:139], v[80:95]
	s_waitcnt lgkmcnt(0)
	v_mfma_f32_32x32x16_bf16 v[80:95], v[230:233], v[140:143], v[80:95]
	v_add_u32_e32 v207, s42, v155
	v_add_u32_e32 v221, v207, v168
	v_add_u32_e32 v207, v207, v167
	ds_read_b128 v[240:243], v207 offset:16384
	ds_read_b128 v[244:247], v207 offset:20480
	ds_read_b128 v[248:251], v207 offset:24576
	ds_read_b128 v[252:255], v207 offset:28672
	ds_read_b128 v[208:211], v221 offset:16384
	ds_read_b128 v[222:225], v221 offset:20480
	ds_read_b128 v[226:229], v221 offset:24576
	ds_read_b128 v[230:233], v221 offset:28672
	s_cbranch_scc1 .LBB0_720
	v_add_u32_e32 v0, s37, v174
	v_add_u32_e32 v186, 62, v0
	v_med3_i32 v5, v186, 0, v214
	v_max_i32_e32 v186, 32, v186
	v_subrev_u32_e32 v186, 32, v186
	v_add_u32_e32 v187, 61, v0
	v_min_u32_e32 v186, 0x80, v186
	v_lshl_add_u32 v193, v186, 2, s2
	v_max_i32_e32 v186, 32, v187
	v_subrev_u32_e32 v186, 32, v186
	v_add_u32_e32 v188, 60, v0
	v_min_u32_e32 v186, 0x80, v186
	v_lshl_add_u32 v201, v186, 2, s2
	v_max_i32_e32 v186, 32, v188
	v_subrev_u32_e32 v186, 32, v186
	v_add_u32_e32 v189, 59, v0
	v_min_u32_e32 v186, 0x80, v186
	v_lshl_add_u32 v202, v186, 2, s2
	v_max_i32_e32 v186, 32, v189
	v_subrev_u32_e32 v186, 32, v186
	v_add_u32_e32 v190, 58, v0
	v_min_u32_e32 v186, 0x80, v186
	v_lshl_add_u32 v203, v186, 2, s2
	v_max_i32_e32 v186, 32, v190
	v_subrev_u32_e32 v186, 32, v186
	v_add_u32_e32 v191, 57, v0
	v_min_u32_e32 v186, 0x80, v186
	v_lshl_add_u32 v204, v186, 2, s2
	v_max_i32_e32 v186, 32, v191
	v_add_u32_e32 v181, 63, v0
	v_subrev_u32_e32 v186, 32, v186
	v_med3_i32 v4, v181, 0, v214
	v_add_u32_e32 v192, 56, v0
	v_max_i32_e32 v181, 32, v181
	v_min_u32_e32 v186, 0x80, v186
	v_add_u32_e32 v194, 47, v0
	v_add_u32_e32 v195, 46, v0
	v_add_u32_e32 v196, 45, v0
	v_add_u32_e32 v197, 44, v0
	v_add_u32_e32 v198, 43, v0
	v_add_u32_e32 v199, 42, v0
	v_add_u32_e32 v200, 41, v0
	v_add_u32_e32 v0, 40, v0
	v_subrev_u32_e32 v181, 32, v181
	v_lshl_add_u32 v205, v186, 2, s2
	v_max_i32_e32 v186, 32, v192
	v_med3_i32 v6, v187, 0, v214
	v_med3_i32 v7, v188, 0, v214
	v_med3_i32 v8, v189, 0, v214
	v_med3_i32 v9, v190, 0, v214
	v_med3_i32 v10, v191, 0, v214
	v_med3_i32 v11, v192, 0, v214
	v_med3_i32 v12, v194, 0, v214
	v_med3_i32 v13, v195, 0, v214
	v_med3_i32 v14, v196, 0, v214
	v_med3_i32 v15, v197, 0, v214
	v_med3_i32 v182, v198, 0, v214
	v_med3_i32 v183, v199, 0, v214
	v_med3_i32 v184, v200, 0, v214
	v_med3_i32 v185, v0, 0, v214
	v_min_u32_e32 v181, 0x80, v181
	v_subrev_u32_e32 v186, 32, v186
	v_lshl_add_u32 v4, v4, 2, s2
	v_lshl_add_u32 v5, v5, 2, s2
	v_lshl_add_u32 v6, v6, 2, s2
	v_lshl_add_u32 v7, v7, 2, s2
	v_lshl_add_u32 v8, v8, 2, s2
	v_lshl_add_u32 v9, v9, 2, s2
	v_lshl_add_u32 v10, v10, 2, s2
	v_lshl_add_u32 v11, v11, 2, s2
	v_lshl_add_u32 v12, v12, 2, s2
	v_lshl_add_u32 v13, v13, 2, s2
	v_lshl_add_u32 v14, v14, 2, s2
	v_lshl_add_u32 v15, v15, 2, s2
	v_lshl_add_u32 v182, v182, 2, s2
	v_lshl_add_u32 v183, v183, 2, s2
	v_lshl_add_u32 v184, v184, 2, s2
	v_lshl_add_u32 v185, v185, 2, s2
	v_lshl_add_u32 v181, v181, 2, s2
	v_min_u32_e32 v186, 0x80, v186
	ds_read_b32 v4, v4
	ds_read_b32 v5, v5
	ds_read_b32 v6, v6
	ds_read_b32 v7, v7
	ds_read_b32 v8, v8
	ds_read_b32 v9, v9
	ds_read_b32 v10, v10
	ds_read_b32 v11, v11
	ds_read_b32 v12, v12
	ds_read_b32 v13, v13
	ds_read_b32 v14, v14
	ds_read_b32 v15, v15
	ds_read_b32 v182, v182
	ds_read_b32 v183, v183
	ds_read_b32 v184, v184
	ds_read_b32 v185, v185
	v_lshl_add_u32 v206, v186, 2, s2
	ds_read_b32 v186, v181
	ds_read_b32 v187, v193
	ds_read_b32 v188, v201
	ds_read_b32 v189, v202
	ds_read_b32 v190, v203
	ds_read_b32 v191, v204
	ds_read_b32 v192, v205
	ds_read_b32 v193, v206
	v_max_i32_e32 v181, 32, v194
	v_max_i32_e32 v194, 32, v195
	v_subrev_u32_e32 v194, 32, v194
	v_min_u32_e32 v194, 0x80, v194
	v_lshl_add_u32 v195, v194, 2, s2
	v_max_i32_e32 v194, 32, v196
	v_subrev_u32_e32 v194, 32, v194
	v_min_u32_e32 v194, 0x80, v194
	v_lshl_add_u32 v196, v194, 2, s2
	v_max_i32_e32 v194, 32, v197
	v_subrev_u32_e32 v194, 32, v194
	v_min_u32_e32 v194, 0x80, v194
	v_lshl_add_u32 v197, v194, 2, s2
	v_max_i32_e32 v194, 32, v198
	v_subrev_u32_e32 v194, 32, v194
	v_min_u32_e32 v194, 0x80, v194
	v_lshl_add_u32 v198, v194, 2, s2
	v_max_i32_e32 v194, 32, v199
	v_subrev_u32_e32 v194, 32, v194
	v_min_u32_e32 v194, 0x80, v194
	v_lshl_add_u32 v199, v194, 2, s2
	v_max_i32_e32 v194, 32, v200
	v_subrev_u32_e32 v181, 32, v181
	v_subrev_u32_e32 v194, 32, v194
	v_max_i32_e32 v0, 32, v0
	v_min_u32_e32 v181, 0x80, v181
	v_min_u32_e32 v194, 0x80, v194
	v_subrev_u32_e32 v0, 32, v0
	v_lshl_add_u32 v181, v181, 2, s2
	v_lshl_add_u32 v200, v194, 2, s2
	v_min_u32_e32 v0, 0x80, v0
	v_lshl_add_u32 v0, v0, 2, s2
	ds_read_b32 v194, v181
	ds_read_b32 v195, v195
	ds_read_b32 v196, v196
	ds_read_b32 v197, v197
	ds_read_b32 v198, v198
	ds_read_b32 v199, v199
	ds_read_b32 v200, v200
	ds_read_b32 v201, v0
	s_waitcnt lgkmcnt(0)
	v_pk_add_f32 v[110:111], v[110:111], v[184:185]
	v_pk_add_f32 v[108:109], v[108:109], v[182:183]
	v_pk_add_f32 v[106:107], v[106:107], v[14:15]
	v_pk_add_f32 v[104:105], v[104:105], v[12:13]
	v_pk_add_f32 v[102:103], v[102:103], v[10:11]
	v_pk_add_f32 v[100:101], v[100:101], v[8:9]
	v_pk_add_f32 v[98:99], v[98:99], v[6:7]
	v_pk_add_f32 v[96:97], v[96:97], v[4:5]
	v_pk_add_f32 v[94:95], v[94:95], v[200:201]
	v_pk_add_f32 v[92:93], v[92:93], v[198:199]
	v_pk_add_f32 v[90:91], v[90:91], v[196:197]
	v_pk_add_f32 v[88:89], v[88:89], v[194:195]
	v_pk_add_f32 v[86:87], v[86:87], v[192:193]
	v_pk_add_f32 v[84:85], v[84:85], v[190:191]
	v_pk_add_f32 v[82:83], v[82:83], v[188:189]
	v_pk_add_f32 v[80:81], v[80:81], v[186:187]

.LBB0_722:
	v_cndmask_b32_e64 v145, v4, v145, s[0:1]
	v_lshrrev_b32_e32 v4, v154, v148
	v_sub_f32_e32 v5, v96, v145
	v_and_b32_e32 v6, 1, v4
	v_exp_f32_e32 v5, v5
	v_cmp_eq_u32_e32 vcc, 1, v6
	v_sub_f32_e32 v6, v97, v145
	v_exp_f32_e32 v6, v6
	v_and_b32_e32 v7, 2, v4
	v_cndmask_b32_e32 v148, 0, v5, vcc
	v_cmp_ne_u32_e32 vcc, 0, v7
	v_and_b32_e32 v7, 4, v4
	v_add_f32_e32 v5, 0, v148
	v_cndmask_b32_e32 v181, 0, v6, vcc
	v_sub_f32_e32 v6, v98, v145
	v_exp_f32_e32 v6, v6
	v_cmp_ne_u32_e32 vcc, 0, v7
	v_and_b32_e32 v7, 8, v4
	v_add_f32_e32 v5, v181, v5
	v_cndmask_b32_e32 v182, 0, v6, vcc
	v_sub_f32_e32 v6, v99, v145
	v_exp_f32_e32 v6, v6
	v_cmp_ne_u32_e32 vcc, 0, v7
	v_and_b32_e32 v7, 16, v4
	v_add_f32_e32 v5, v182, v5
	v_cndmask_b32_e32 v183, 0, v6, vcc
	v_sub_f32_e32 v6, v100, v145
	v_exp_f32_e32 v6, v6
	v_cmp_ne_u32_e32 vcc, 0, v7
	v_and_b32_e32 v7, 32, v4
	v_add_f32_e32 v5, v183, v5
	v_cndmask_b32_e32 v184, 0, v6, vcc
	v_sub_f32_e32 v6, v101, v145
	v_exp_f32_e32 v6, v6
	v_cmp_ne_u32_e32 vcc, 0, v7
	v_and_b32_e32 v7, 64, v4
	v_add_f32_e32 v5, v184, v5
	v_cndmask_b32_e32 v185, 0, v6, vcc
	v_sub_f32_e32 v6, v102, v145
	v_exp_f32_e32 v6, v6
	v_cmp_ne_u32_e32 vcc, 0, v7
	v_and_b32_e32 v7, 0x80, v4
	v_add_f32_e32 v5, v185, v5
	v_cndmask_b32_e32 v186, 0, v6, vcc
	v_sub_f32_e32 v6, v103, v145
	v_exp_f32_e32 v6, v6
	v_cmp_ne_u32_e32 vcc, 0, v7
	v_and_b32_e32 v7, 0x10000, v4
	v_add_f32_e32 v5, v186, v5
	v_cndmask_b32_e32 v187, 0, v6, vcc
	v_sub_f32_e32 v6, v104, v145
	v_exp_f32_e32 v6, v6
	v_cmp_ne_u32_e32 vcc, 0, v7
	v_and_b32_e32 v7, 0x20000, v4
	v_add_f32_e32 v5, v187, v5
	v_cndmask_b32_e32 v96, 0, v6, vcc
	v_sub_f32_e32 v6, v105, v145
	v_exp_f32_e32 v6, v6
	v_cmp_ne_u32_e32 vcc, 0, v7
	v_and_b32_e32 v7, 0x40000, v4
	v_add_f32_e32 v5, v96, v5
	v_cndmask_b32_e32 v97, 0, v6, vcc
	v_sub_f32_e32 v6, v106, v145
	v_exp_f32_e32 v6, v6
	v_cmp_ne_u32_e32 vcc, 0, v7
	v_and_b32_e32 v7, 0x80000, v4
	v_add_f32_e32 v5, v97, v5
	v_cndmask_b32_e32 v98, 0, v6, vcc
	v_sub_f32_e32 v6, v107, v145
	v_exp_f32_e32 v6, v6
	v_cmp_ne_u32_e32 vcc, 0, v7
	v_and_b32_e32 v7, 0x100000, v4
	v_add_f32_e32 v5, v98, v5
	v_cndmask_b32_e32 v99, 0, v6, vcc
	v_sub_f32_e32 v6, v108, v145
	v_exp_f32_e32 v6, v6
	v_cmp_ne_u32_e32 vcc, 0, v7
	v_and_b32_e32 v7, 0x200000, v4
	v_add_f32_e32 v5, v99, v5
	v_cndmask_b32_e32 v100, 0, v6, vcc
	v_sub_f32_e32 v6, v109, v145
	v_exp_f32_e32 v6, v6
	v_cmp_ne_u32_e32 vcc, 0, v7
	v_and_b32_e32 v7, 0x400000, v4
	v_add_f32_e32 v5, v100, v5
	v_cndmask_b32_e32 v101, 0, v6, vcc
	v_sub_f32_e32 v6, v110, v145
	v_exp_f32_e32 v6, v6
	v_cmp_ne_u32_e32 vcc, 0, v7
	v_and_b32_e32 v4, 0x800000, v4
	v_add_f32_e32 v5, v101, v5
	v_cndmask_b32_e32 v102, 0, v6, vcc
	v_sub_f32_e32 v6, v111, v145
	v_exp_f32_e32 v6, v6
	v_cmp_ne_u32_e32 vcc, 0, v4
	v_add_f32_e32 v5, v102, v5
	v_lshrrev_b32_e32 v12, v154, v149
	v_cndmask_b32_e32 v103, 0, v6, vcc
	v_add_f32_e32 v4, v103, v5
	v_sub_f32_e32 v5, v80, v145
	v_exp_f32_e32 v5, v5
	v_and_b32_e32 v6, 1, v12
	v_cmp_eq_u32_e32 vcc, 1, v6
	v_and_b32_e32 v6, 2, v12
	v_and_b32_e32 v7, 0x20000, v12
	v_cndmask_b32_e32 v13, 0, v5, vcc
	v_sub_f32_e32 v5, v81, v145
	v_exp_f32_e32 v5, v5
	v_cmp_ne_u32_e32 vcc, 0, v6
	v_and_b32_e32 v6, 4, v12
	v_and_b32_e32 v8, 0x40000, v12
	v_cndmask_b32_e32 v14, 0, v5, vcc
	v_sub_f32_e32 v5, v82, v145
	v_exp_f32_e32 v5, v5
	v_cmp_ne_u32_e32 vcc, 0, v6
	v_and_b32_e32 v6, 8, v12
	v_add_f32_e32 v4, v13, v4
	v_cndmask_b32_e32 v15, 0, v5, vcc
	v_sub_f32_e32 v5, v83, v145
	v_exp_f32_e32 v5, v5
	v_cmp_ne_u32_e32 vcc, 0, v6
	v_and_b32_e32 v6, 16, v12
	v_add_f32_e32 v4, v14, v4
	v_cndmask_b32_e32 v80, 0, v5, vcc
	v_sub_f32_e32 v5, v84, v145
	v_exp_f32_e32 v5, v5
	v_cmp_ne_u32_e32 vcc, 0, v6
	v_and_b32_e32 v6, 32, v12
	v_add_f32_e32 v4, v15, v4
	v_cndmask_b32_e32 v81, 0, v5, vcc
	v_sub_f32_e32 v5, v85, v145
	v_exp_f32_e32 v5, v5
	v_cmp_ne_u32_e32 vcc, 0, v6
	v_and_b32_e32 v6, 64, v12
	v_and_b32_e32 v9, 0x80000, v12
	v_cndmask_b32_e32 v82, 0, v5, vcc
	v_sub_f32_e32 v5, v86, v145
	v_exp_f32_e32 v5, v5
	v_cmp_ne_u32_e32 vcc, 0, v6
	v_and_b32_e32 v6, 0x80, v12
	v_add_f32_e32 v4, v80, v4
	v_cndmask_b32_e32 v83, 0, v5, vcc
	v_sub_f32_e32 v5, v87, v145
	v_exp_f32_e32 v5, v5
	v_cmp_ne_u32_e32 vcc, 0, v6
	v_and_b32_e32 v6, 0x10000, v12
	v_and_b32_e32 v10, 0x100000, v12
	v_cndmask_b32_e32 v84, 0, v5, vcc
	v_sub_f32_e32 v5, v88, v145
	v_exp_f32_e32 v5, v5
	v_cmp_ne_u32_e32 vcc, 0, v6
	v_sub_f32_e32 v6, v89, v145
	v_exp_f32_e32 v6, v6
	v_cndmask_b32_e32 v5, 0, v5, vcc
	v_cmp_ne_u32_e32 vcc, 0, v7
	v_sub_f32_e32 v7, v90, v145
	v_exp_f32_e32 v7, v7
	v_cndmask_b32_e32 v6, 0, v6, vcc
	v_cmp_ne_u32_e32 vcc, 0, v8
	v_sub_f32_e32 v8, v91, v145
	v_exp_f32_e32 v8, v8
	v_cndmask_b32_e32 v7, 0, v7, vcc
	v_cmp_ne_u32_e32 vcc, 0, v9
	v_sub_f32_e32 v9, v92, v145
	v_add_f32_e32 v4, v81, v4
	v_cndmask_b32_e32 v8, 0, v8, vcc
	v_exp_f32_e32 v9, v9
	v_cmp_ne_u32_e32 vcc, 0, v10
	v_sub_f32_e32 v10, v93, v145
	v_add_f32_e32 v4, v82, v4
	v_exp_f32_e32 v10, v10
	v_add_f32_e32 v4, v83, v4
	v_add_f32_e32 v4, v84, v4
	v_and_b32_e32 v11, 0x200000, v12
	v_add_f32_e32 v4, v5, v4
	v_cndmask_b32_e32 v9, 0, v9, vcc
	v_cmp_ne_u32_e32 vcc, 0, v11
	v_sub_f32_e32 v11, v94, v145
	v_and_b32_e32 v85, 0x400000, v12
	v_add_f32_e32 v4, v6, v4
	v_cndmask_b32_e32 v10, 0, v10, vcc
	v_exp_f32_e32 v11, v11
	v_cmp_ne_u32_e32 vcc, 0, v85
	v_sub_f32_e32 v85, v95, v145
	v_add_f32_e32 v4, v7, v4
	v_exp_f32_e32 v85, v85
	v_add_f32_e32 v4, v8, v4
	v_add_f32_e32 v4, v9, v4
	v_and_b32_e32 v12, 0x800000, v12
	v_add_f32_e32 v4, v10, v4
	v_cndmask_b32_e32 v11, 0, v11, vcc
	v_cmp_ne_u32_e32 vcc, 0, v12
	v_add_f32_e32 v4, v11, v4
	v_cndmask_b32_e64 v0, v0, 1.0, s[0:1]
	v_cndmask_b32_e32 v12, 0, v85, vcc
	v_add_f32_e32 v4, v12, v4
	v_fmac_f32_e32 v4, v180, v0
	v_add_u32_e32 v0, s42, v155
	v_add_u32_e32 v85, v0, v169
	v_add_u32_e32 v0, v0, v170
	v_cvt_pk_bf16_f32 v86, v148, v181
	v_cvt_pk_bf16_f32 v87, v182, v183
	v_cvt_pk_bf16_f32 v88, v184, v185
	v_cvt_pk_bf16_f32 v89, v186, v187
	v_cvt_pk_bf16_f32 v7, v7, v8
	v_cvt_pk_bf16_f32 v8, v9, v10
	v_cvt_pk_bf16_f32 v9, v11, v12
	v_cvt_pk_bf16_f32 v6, v5, v6
	v_mov_b32_e32 v180, v4
	s_waitcnt lgkmcnt(0)
	v_mfma_f32_32x32x16_bf16 v[64:79], v[240:243], v[86:89], v[64:79]
	ds_read_b128 v[240:243], v85 offset:16384
	v_mfma_f32_32x32x16_bf16 v[48:63], v[244:247], v[86:89], v[48:63]
	ds_read_b128 v[244:247], v85 offset:20480
	v_mfma_f32_32x32x16_bf16 v[32:47], v[248:251], v[86:89], v[32:47]
	ds_read_b128 v[248:251], v85 offset:24576
	v_mfma_f32_32x32x16_bf16 v[16:31], v[252:255], v[86:89], v[16:31]
	ds_read_b128 v[252:255], v85 offset:28672
	v_cvt_pk_bf16_f32 v86, v96, v97
	v_cvt_pk_bf16_f32 v87, v98, v99
	v_cvt_pk_bf16_f32 v88, v100, v101
	v_cvt_pk_bf16_f32 v89, v102, v103
	s_nop 1
	v_mfma_f32_32x32x16_bf16 v[64:79], v[208:211], v[86:89], v[64:79]
	ds_read_b128 v[208:211], v0 offset:16384
	v_mfma_f32_32x32x16_bf16 v[48:63], v[222:225], v[86:89], v[48:63]
	ds_read_b128 v[222:225], v0 offset:20480
	v_mfma_f32_32x32x16_bf16 v[32:47], v[226:229], v[86:89], v[32:47]
	ds_read_b128 v[226:229], v0 offset:24576
	v_mfma_f32_32x32x16_bf16 v[16:31], v[230:233], v[86:89], v[16:31]
	ds_read_b128 v[230:233], v0 offset:28672
	v_cvt_pk_bf16_f32 v86, v13, v14
	v_cvt_pk_bf16_f32 v87, v15, v80
	v_cvt_pk_bf16_f32 v88, v81, v82
	v_cvt_pk_bf16_f32 v89, v83, v84
	s_nop 1
	s_waitcnt lgkmcnt(7)
	v_mfma_f32_32x32x16_bf16 v[64:79], v[240:243], v[86:89], v[64:79]
	s_waitcnt lgkmcnt(6)
	v_mfma_f32_32x32x16_bf16 v[48:63], v[244:247], v[86:89], v[48:63]
	s_waitcnt lgkmcnt(5)
	v_mfma_f32_32x32x16_bf16 v[32:47], v[248:251], v[86:89], v[32:47]
	s_waitcnt lgkmcnt(4)
	v_mfma_f32_32x32x16_bf16 v[16:31], v[252:255], v[86:89], v[16:31]
	s_waitcnt lgkmcnt(3)
	v_mfma_f32_32x32x16_bf16 v[64:79], v[208:211], v[6:9], v[64:79]
	s_waitcnt lgkmcnt(2)
	v_mfma_f32_32x32x16_bf16 v[48:63], v[222:225], v[6:9], v[48:63]
	s_waitcnt lgkmcnt(1)
	v_mfma_f32_32x32x16_bf16 v[32:47], v[226:229], v[6:9], v[32:47]
	s_waitcnt lgkmcnt(0)
	v_mfma_f32_32x32x16_bf16 v[16:31], v[230:233], v[6:9], v[16:31]
.LBB0_723:
	s_add_i32 s41, s41, 1
	s_add_i32 s0, s40, 1
	s_cmp_lg_u32 s40, 2
	s_cselect_b32 s40, s0, 0
	s_sub_i32 s37, s37, 64
	s_cmp_eq_u32 s34, s41
	v_lshl_add_u64 v[146:147], v[146:147], 0, 8
	s_cbranch_scc1 .LBB0_713
	s_waitcnt vmcnt(4)
	v_mov_b64_e32 v[148:149], v[2:3]
	s_branch .LBB0_715

	.amdhsa_kernel _Z14fwd_megakernel6Params
		.amdhsa_group_segment_fixed_size 0
		.amdhsa_private_segment_fixed_size 0
		.amdhsa_kernarg_size 376
		.amdhsa_user_sgpr_count 2
		.amdhsa_user_sgpr_dispatch_ptr 0
		.amdhsa_user_sgpr_queue_ptr 0
		.amdhsa_user_sgpr_kernarg_segment_ptr 1
		.amdhsa_user_sgpr_dispatch_id 0
		.amdhsa_user_sgpr_kernarg_preload_length 0
		.amdhsa_user_sgpr_kernarg_preload_offset 0
		.amdhsa_user_sgpr_private_segment_size 0
		.amdhsa_uses_dynamic_stack 0
		.amdhsa_enable_private_segment 0
		.amdhsa_system_sgpr_workgroup_id_x 1
		.amdhsa_system_sgpr_workgroup_id_y 0
		.amdhsa_system_sgpr_workgroup_id_z 0
		.amdhsa_system_sgpr_workgroup_info 0
		.amdhsa_system_vgpr_workitem_id 2
		.amdhsa_next_free_vgpr 256
		.amdhsa_next_free_sgpr 98
		.amdhsa_accum_offset 256
		.amdhsa_reserve_vcc 1
		.amdhsa_float_round_mode_32 0
		.amdhsa_float_round_mode_16_64 0
		.amdhsa_float_denorm_mode_32 3
		.amdhsa_float_denorm_mode_16_64 3
		.amdhsa_dx10_clamp 1
		.amdhsa_ieee_mode 1
		.amdhsa_fp16_overflow 0
		.amdhsa_tg_split 0
		.amdhsa_exception_fp_ieee_invalid_op 0
		.amdhsa_exception_fp_denorm_src 0
		.amdhsa_exception_fp_ieee_div_zero 0
		.amdhsa_exception_fp_ieee_overflow 0
		.amdhsa_exception_fp_ieee_underflow 0
		.amdhsa_exception_fp_ieee_inexact 0
		.amdhsa_exception_int_div_zero 0
	.end_amdhsa_kernel

amdhsa.kernels:
  - .agpr_count:     0
    .args:
      - .offset:         0
        .size:           120
        .value_kind:     by_value
      - .offset:         120
        .size:           4
        .value_kind:     hidden_block_count_x
      - .offset:         124
        .size:           4
        .value_kind:     hidden_block_count_y
      - .offset:         128
        .size:           4
        .value_kind:     hidden_block_count_z
      - .offset:         132
        .size:           2
        .value_kind:     hidden_group_size_x
      - .offset:         134
        .size:           2
        .value_kind:     hidden_group_size_y
      - .offset:         136
        .size:           2
        .value_kind:     hidden_group_size_z
      - .offset:         138
        .size:           2
        .value_kind:     hidden_remainder_x
      - .offset:         140
        .size:           2
        .value_kind:     hidden_remainder_y
      - .offset:         142
        .size:           2
        .value_kind:     hidden_remainder_z
      - .offset:         160
        .size:           8
        .value_kind:     hidden_global_offset_x
      - .offset:         168
        .size:           8
        .value_kind:     hidden_global_offset_y
      - .offset:         176
        .size:           8
        .value_kind:     hidden_global_offset_z
      - .offset:         184
        .size:           2
        .value_kind:     hidden_grid_dims
      - .offset:         208
        .size:           8
        .value_kind:     hidden_multigrid_sync_arg
      - .offset:         240
        .size:           4
        .value_kind:     hidden_dynamic_lds_size
    .group_segment_fixed_size: 0
    .kernarg_segment_align: 8
    .kernarg_segment_size: 376
    .language:       OpenCL C
    .language_version:
      - 2
      - 0
    .max_flat_workgroup_size: 512
    .name:           _Z14fwd_megakernel6Params
    .private_segment_fixed_size: 0
    .sgpr_count:     104
    .sgpr_spill_count: 375
    .symbol:         _Z14fwd_megakernel6Params.kd
    .uniform_work_group_size: 1
    .uses_dynamic_stack: false
    .vgpr_count:     256
    .vgpr_spill_count: 0
    .wavefront_size: 64
